# mix-in lru-x / gelu / rope epilogues: blocks (0,1) and (2,3) paired via v_permlane16_swap, two dwordx4 stores per row block instead of four dwordx2
# speedup vs baseline: 1.0275x; 1.0043x over previous
.LBB0_409:
	s_or_b64 exec, exec, s[2:3]
	s_waitcnt lgkmcnt(0)
	v_add_f32_e32 v10, v10, v11
	v_fmamk_f32 v10, v10, 0x3c800000, v192
	v_mul_f32_e32 v11, 0x4b800000, v10
	v_cmp_gt_f32_e32 vcc, s58, v10
	v_lshl_add_u64 v[0:1], v[0:1], 0, v[144:145]
	s_nop 0
	v_cndmask_b32_e32 v10, v10, v11, vcc
	v_rsq_f32_e32 v10, v10
	s_nop 0
	v_mul_f32_e32 v11, 0x45800000, v10
	v_cndmask_b32_e32 v10, v10, v11, vcc
	v_pk_mul_f32 v[34:35], v[34:35], v[10:11] op_sel_hi:[1,0]
	v_pk_mul_f32 v[12:13], v[38:39], v[10:11] op_sel_hi:[1,0]
	v_pk_mul_f32 v[32:33], v[36:37], v[10:11] op_sel_hi:[1,0]
	v_pk_mul_f32 v[34:35], v[138:139], v[34:35]
	v_pk_mul_f32 v[14:15], v[40:41], v[10:11] op_sel_hi:[1,0]
	v_pk_mul_f32 v[12:13], v[142:143], v[12:13]
	v_pk_mul_f32 v[32:33], v[136:137], v[32:33]
	v_pk_mul_f32 v[2:3], v[2:3], v[10:11] op_sel_hi:[1,0]
	s_waitcnt vmcnt(0)
	v_pk_mul_f32 v[36:37], v[30:31], v[34:35]
	v_pk_mul_f32 v[14:15], v[140:141], v[14:15]
	v_pk_mul_f32 v[6:7], v[6:7], v[10:11] op_sel_hi:[1,0]
	v_pk_mul_f32 v[8:9], v[8:9], v[10:11] op_sel_hi:[1,0]
	v_pk_mul_f32 v[4:5], v[4:5], v[10:11] op_sel_hi:[1,0]
	v_pk_mul_f32 v[2:3], v[130:131], v[2:3]
	v_pk_mul_f32 v[10:11], v[28:29], v[32:33]
	v_pk_fma_f32 v[36:37], v[22:23], v[12:13], v[36:37] neg_lo:[0,0,1] neg_hi:[0,0,1]
	v_pk_mul_f32 v[12:13], v[30:31], v[12:13]
	v_pk_mul_f32 v[6:7], v[134:135], v[6:7]
	v_pk_mul_f32 v[4:5], v[128:129], v[4:5]
	v_pk_fma_f32 v[10:11], v[20:21], v[14:15], v[10:11] neg_lo:[0,0,1] neg_hi:[0,0,1]
	v_pk_mul_f32 v[14:15], v[28:29], v[14:15]
	v_pk_fma_f32 v[12:13], v[22:23], v[34:35], v[12:13]
	v_pk_mul_f32 v[22:23], v[26:27], v[2:3]
	v_pk_mul_f32 v[8:9], v[132:133], v[8:9]
	v_pk_fma_f32 v[14:15], v[20:21], v[32:33], v[14:15]
	v_pk_mul_f32 v[20:21], v[24:25], v[4:5]
	v_pk_fma_f32 v[22:23], v[18:19], v[6:7], v[22:23] neg_lo:[0,0,1] neg_hi:[0,0,1]
	v_pk_mul_f32 v[6:7], v[26:27], v[6:7]
	v_pk_fma_f32 v[20:21], v[16:17], v[8:9], v[20:21] neg_lo:[0,0,1] neg_hi:[0,0,1]
	v_pk_mul_f32 v[8:9], v[24:25], v[8:9]
	v_pk_fma_f32 v[2:3], v[18:19], v[2:3], v[6:7]
	v_cvt_pk_bf16_f32 v6, v10, v11
	v_cvt_pk_bf16_f32 v7, v36, v37
	v_pk_fma_f32 v[4:5], v[16:17], v[4:5], v[8:9]
	v_mov_b32_e32 v248, v6
	v_mov_b32_e32 v249, v7
	v_cvt_pk_bf16_f32 v6, v14, v15
	v_cvt_pk_bf16_f32 v7, v12, v13
	v_mov_b32_e32 v250, v6
	v_mov_b32_e32 v251, v7
	v_cvt_pk_bf16_f32 v6, v20, v21
	v_cvt_pk_bf16_f32 v7, v22, v23
	v_mov_b32_e32 v244, v6
	v_mov_b32_e32 v245, v7
	v_cvt_pk_bf16_f32 v4, v4, v5
	v_cvt_pk_bf16_f32 v5, v2, v3
	v_mov_b32_e32 v246, v4
	v_mov_b32_e32 v247, v5
	v_and_b32_e32 v242, 16, v190
	v_mul_u32_u24_e32 v242, 3, v242
	v_lshrrev_b32_e32 v242, 1, v242
	v_mov_b32_e32 v243, 0
	v_lshl_add_u64 v[240:241], v[0:1], 0, v[242:243]
	v_permlane16_swap_b32 v248, v250
	v_permlane16_swap_b32 v249, v251
	v_permlane16_swap_b32 v244, v246
	v_permlane16_swap_b32 v245, v247
	flat_store_dwordx4 v[240:241], v[248:251]
	flat_store_dwordx4 v[240:241], v[244:247] offset:64

.LBB0_429:
	s_andn2_b64 vcc, exec, s[2:3]
	s_cbranch_vccnz .LBB0_431
	v_lshlrev_b32_e32 v130, 2, v159
	v_mov_b32_e32 v155, v145
	v_lshl_or_b32 v130, v160, 9, v130
	v_lshl_add_u64 v[128:129], v[154:155], 1, s[20:21]
	v_add_u32_e32 v155, 0x20800, v130
	ds_read_b32 v132, v155
	v_or_b32_e32 v130, s26, v159
	v_lshl_add_u32 v130, v160, 7, v130
	v_lshl_add_u64 v[128:129], v[128:129], 0, v[144:145]
	s_mov_b64 s[2:3], 0x91df200
	v_ashrrev_i32_e32 v131, 31, v130
	v_lshl_add_u64 v[128:129], v[128:129], 0, s[2:3]
	s_waitcnt lgkmcnt(0)
	v_pk_mul_f32 v[134:135], v[126:127], v[132:133] op_sel_hi:[1,0]
	v_pk_mul_f32 v[136:137], v[124:125], v[132:133] op_sel_hi:[1,0]
	v_lshlrev_b64 v[156:157], 10, v[130:131]
	v_pk_mul_f32 v[138:139], v[122:123], v[132:133] op_sel_hi:[1,0]
	v_pk_mul_f32 v[140:141], v[120:121], v[132:133] op_sel_hi:[1,0]
	v_pk_mul_f32 v[142:143], v[118:119], v[132:133] op_sel_hi:[1,0]
	v_pk_mul_f32 v[146:147], v[116:117], v[132:133] op_sel_hi:[1,0]
	v_pk_mul_f32 v[148:149], v[114:115], v[132:133] op_sel_hi:[1,0]
	v_pk_mul_f32 v[132:133], v[112:113], v[132:133] op_sel_hi:[1,0]
	v_lshl_add_u64 v[156:157], v[128:129], 0, v[156:157]
	v_cvt_pk_bf16_f32 v136, v136, v137
	v_cvt_pk_bf16_f32 v137, v134, v135
	v_cvt_pk_bf16_f32 v134, v140, v141
	v_cvt_pk_bf16_f32 v135, v138, v139
	s_waitcnt vmcnt(0)
	v_mov_b32_e32 v248, v136
	v_mov_b32_e32 v249, v137
	v_mov_b32_e32 v250, v134
	v_mov_b32_e32 v251, v135
	v_cvt_pk_bf16_f32 v134, v146, v147
	v_cvt_pk_bf16_f32 v135, v142, v143
	v_mov_b32_e32 v244, v134
	v_mov_b32_e32 v245, v135
	v_cvt_pk_bf16_f32 v132, v132, v133
	v_cvt_pk_bf16_f32 v133, v148, v149
	v_mov_b32_e32 v246, v132
	v_mov_b32_e32 v247, v133
	v_and_b32_e32 v242, 16, v190
	v_mul_u32_u24_e32 v242, 3, v242
	v_lshrrev_b32_e32 v242, 1, v242
	v_mov_b32_e32 v243, 0
	v_lshl_add_u64 v[240:241], v[156:157], 0, v[242:243]
	v_permlane16_swap_b32 v248, v250
	v_permlane16_swap_b32 v249, v251
	v_permlane16_swap_b32 v244, v246
	v_permlane16_swap_b32 v245, v247
	flat_store_dwordx4 v[240:241], v[248:251]
	flat_store_dwordx4 v[240:241], v[244:247] offset:64
	ds_read_b32 v132, v155 offset:64
	v_or_b32_e32 v134, 16, v130
	v_ashrrev_i32_e32 v135, 31, v134
	v_lshlrev_b64 v[134:135], 10, v[134:135]
	v_lshl_add_u64 v[134:135], v[128:129], 0, v[134:135]
	s_waitcnt lgkmcnt(0)
	v_pk_mul_f32 v[136:137], v[110:111], v[132:133] op_sel_hi:[1,0]
	v_pk_mul_f32 v[138:139], v[108:109], v[132:133] op_sel_hi:[1,0]
	v_pk_mul_f32 v[140:141], v[106:107], v[132:133] op_sel_hi:[1,0]
	v_pk_mul_f32 v[142:143], v[104:105], v[132:133] op_sel_hi:[1,0]
	v_pk_mul_f32 v[146:147], v[102:103], v[132:133] op_sel_hi:[1,0]
	v_pk_mul_f32 v[148:149], v[100:101], v[132:133] op_sel_hi:[1,0]
	v_pk_mul_f32 v[156:157], v[98:99], v[132:133] op_sel_hi:[1,0]
	v_pk_mul_f32 v[132:133], v[96:97], v[132:133] op_sel_hi:[1,0]
	v_cvt_pk_bf16_f32 v138, v138, v139
	v_cvt_pk_bf16_f32 v139, v136, v137
	v_cvt_pk_bf16_f32 v136, v142, v143
	v_cvt_pk_bf16_f32 v137, v140, v141
	v_mov_b32_e32 v248, v138
	v_mov_b32_e32 v249, v139
	v_mov_b32_e32 v250, v136
	v_mov_b32_e32 v251, v137
	v_cvt_pk_bf16_f32 v136, v148, v149
	v_cvt_pk_bf16_f32 v137, v146, v147
	v_mov_b32_e32 v244, v136
	v_mov_b32_e32 v245, v137
	v_cvt_pk_bf16_f32 v132, v132, v133
	v_cvt_pk_bf16_f32 v133, v156, v157
	v_mov_b32_e32 v246, v132
	v_mov_b32_e32 v247, v133
	v_and_b32_e32 v242, 16, v190
	v_mul_u32_u24_e32 v242, 3, v242
	v_lshrrev_b32_e32 v242, 1, v242
	v_mov_b32_e32 v243, 0
	v_lshl_add_u64 v[240:241], v[134:135], 0, v[242:243]
	v_permlane16_swap_b32 v248, v250
	v_permlane16_swap_b32 v249, v251
	v_permlane16_swap_b32 v244, v246
	v_permlane16_swap_b32 v245, v247
	flat_store_dwordx4 v[240:241], v[248:251]
	flat_store_dwordx4 v[240:241], v[244:247] offset:64
	ds_read_b32 v132, v155 offset:128
	v_or_b32_e32 v134, 32, v130
	v_ashrrev_i32_e32 v135, 31, v134
	v_lshlrev_b64 v[134:135], 10, v[134:135]
	v_lshl_add_u64 v[134:135], v[128:129], 0, v[134:135]
	s_waitcnt lgkmcnt(0)
	v_pk_mul_f32 v[136:137], v[94:95], v[132:133] op_sel_hi:[1,0]
	v_pk_mul_f32 v[138:139], v[92:93], v[132:133] op_sel_hi:[1,0]
	v_pk_mul_f32 v[140:141], v[90:91], v[132:133] op_sel_hi:[1,0]
	v_pk_mul_f32 v[142:143], v[88:89], v[132:133] op_sel_hi:[1,0]
	v_pk_mul_f32 v[146:147], v[86:87], v[132:133] op_sel_hi:[1,0]
	v_pk_mul_f32 v[148:149], v[84:85], v[132:133] op_sel_hi:[1,0]
	v_pk_mul_f32 v[156:157], v[82:83], v[132:133] op_sel_hi:[1,0]
	v_pk_mul_f32 v[132:133], v[80:81], v[132:133] op_sel_hi:[1,0]
	v_cvt_pk_bf16_f32 v138, v138, v139
	v_cvt_pk_bf16_f32 v139, v136, v137
	v_cvt_pk_bf16_f32 v136, v142, v143
	v_cvt_pk_bf16_f32 v137, v140, v141
	v_mov_b32_e32 v248, v138
	v_mov_b32_e32 v249, v139
	v_mov_b32_e32 v250, v136
	v_mov_b32_e32 v251, v137
	v_cvt_pk_bf16_f32 v136, v148, v149
	v_cvt_pk_bf16_f32 v137, v146, v147
	v_mov_b32_e32 v244, v136
	v_mov_b32_e32 v245, v137
	v_cvt_pk_bf16_f32 v132, v132, v133
	v_cvt_pk_bf16_f32 v133, v156, v157
	v_mov_b32_e32 v246, v132
	v_mov_b32_e32 v247, v133
	v_and_b32_e32 v242, 16, v190
	v_mul_u32_u24_e32 v242, 3, v242
	v_lshrrev_b32_e32 v242, 1, v242
	v_mov_b32_e32 v243, 0
	v_lshl_add_u64 v[240:241], v[134:135], 0, v[242:243]
	v_permlane16_swap_b32 v248, v250
	v_permlane16_swap_b32 v249, v251
	v_permlane16_swap_b32 v244, v246
	v_permlane16_swap_b32 v245, v247
	flat_store_dwordx4 v[240:241], v[248:251]
	flat_store_dwordx4 v[240:241], v[244:247] offset:64
	ds_read_b32 v132, v155 offset:192
	v_or_b32_e32 v134, 48, v130
	v_ashrrev_i32_e32 v135, 31, v134
	v_lshlrev_b64 v[134:135], 10, v[134:135]
	v_lshl_add_u64 v[134:135], v[128:129], 0, v[134:135]
	s_waitcnt lgkmcnt(0)
	v_pk_mul_f32 v[136:137], v[78:79], v[132:133] op_sel_hi:[1,0]
	v_pk_mul_f32 v[138:139], v[76:77], v[132:133] op_sel_hi:[1,0]
	v_pk_mul_f32 v[140:141], v[74:75], v[132:133] op_sel_hi:[1,0]
	v_pk_mul_f32 v[142:143], v[72:73], v[132:133] op_sel_hi:[1,0]
	v_pk_mul_f32 v[146:147], v[70:71], v[132:133] op_sel_hi:[1,0]
	v_pk_mul_f32 v[148:149], v[68:69], v[132:133] op_sel_hi:[1,0]
	v_pk_mul_f32 v[156:157], v[66:67], v[132:133] op_sel_hi:[1,0]
	v_pk_mul_f32 v[132:133], v[64:65], v[132:133] op_sel_hi:[1,0]
	v_cvt_pk_bf16_f32 v138, v138, v139
	v_cvt_pk_bf16_f32 v139, v136, v137
	v_cvt_pk_bf16_f32 v136, v142, v143
	v_cvt_pk_bf16_f32 v137, v140, v141
	v_mov_b32_e32 v248, v138
	v_mov_b32_e32 v249, v139
	v_mov_b32_e32 v250, v136
	v_mov_b32_e32 v251, v137
	v_cvt_pk_bf16_f32 v136, v148, v149
	v_cvt_pk_bf16_f32 v137, v146, v147
	v_mov_b32_e32 v244, v136
	v_mov_b32_e32 v245, v137
	v_cvt_pk_bf16_f32 v132, v132, v133
	v_cvt_pk_bf16_f32 v133, v156, v157
	v_mov_b32_e32 v246, v132
	v_mov_b32_e32 v247, v133
	v_and_b32_e32 v242, 16, v190
	v_mul_u32_u24_e32 v242, 3, v242
	v_lshrrev_b32_e32 v242, 1, v242
	v_mov_b32_e32 v243, 0
	v_lshl_add_u64 v[240:241], v[134:135], 0, v[242:243]
	v_permlane16_swap_b32 v248, v250
	v_permlane16_swap_b32 v249, v251
	v_permlane16_swap_b32 v244, v246
	v_permlane16_swap_b32 v245, v247
	flat_store_dwordx4 v[240:241], v[248:251]
	flat_store_dwordx4 v[240:241], v[244:247] offset:64
	ds_read_b32 v132, v155 offset:256
	v_or_b32_e32 v134, 64, v130
	v_ashrrev_i32_e32 v135, 31, v134
	v_lshlrev_b64 v[134:135], 10, v[134:135]
	v_lshl_add_u64 v[134:135], v[128:129], 0, v[134:135]
	s_waitcnt lgkmcnt(0)
	v_pk_mul_f32 v[136:137], v[62:63], v[132:133] op_sel_hi:[1,0]
	v_pk_mul_f32 v[138:139], v[60:61], v[132:133] op_sel_hi:[1,0]
	v_pk_mul_f32 v[140:141], v[58:59], v[132:133] op_sel_hi:[1,0]
	v_pk_mul_f32 v[142:143], v[56:57], v[132:133] op_sel_hi:[1,0]
	v_pk_mul_f32 v[146:147], v[54:55], v[132:133] op_sel_hi:[1,0]
	v_pk_mul_f32 v[148:149], v[52:53], v[132:133] op_sel_hi:[1,0]
	v_pk_mul_f32 v[156:157], v[50:51], v[132:133] op_sel_hi:[1,0]
	v_pk_mul_f32 v[132:133], v[48:49], v[132:133] op_sel_hi:[1,0]
	v_cvt_pk_bf16_f32 v138, v138, v139
	v_cvt_pk_bf16_f32 v139, v136, v137
	v_cvt_pk_bf16_f32 v136, v142, v143
	v_cvt_pk_bf16_f32 v137, v140, v141
	v_mov_b32_e32 v248, v138
	v_mov_b32_e32 v249, v139
	v_mov_b32_e32 v250, v136
	v_mov_b32_e32 v251, v137
	v_cvt_pk_bf16_f32 v136, v148, v149
	v_cvt_pk_bf16_f32 v137, v146, v147
	v_mov_b32_e32 v244, v136
	v_mov_b32_e32 v245, v137
	v_cvt_pk_bf16_f32 v132, v132, v133
	v_cvt_pk_bf16_f32 v133, v156, v157
	v_mov_b32_e32 v246, v132
	v_mov_b32_e32 v247, v133
	v_and_b32_e32 v242, 16, v190
	v_mul_u32_u24_e32 v242, 3, v242
	v_lshrrev_b32_e32 v242, 1, v242
	v_mov_b32_e32 v243, 0
	v_lshl_add_u64 v[240:241], v[134:135], 0, v[242:243]
	v_permlane16_swap_b32 v248, v250
	v_permlane16_swap_b32 v249, v251
	v_permlane16_swap_b32 v244, v246
	v_permlane16_swap_b32 v245, v247
	flat_store_dwordx4 v[240:241], v[248:251]
	flat_store_dwordx4 v[240:241], v[244:247] offset:64
	ds_read_b32 v132, v155 offset:320
	v_or_b32_e32 v134, 0x50, v130
	v_ashrrev_i32_e32 v135, 31, v134
	v_lshlrev_b64 v[134:135], 10, v[134:135]
	v_lshl_add_u64 v[134:135], v[128:129], 0, v[134:135]
	s_waitcnt lgkmcnt(0)
	v_pk_mul_f32 v[136:137], v[46:47], v[132:133] op_sel_hi:[1,0]
	v_pk_mul_f32 v[138:139], v[44:45], v[132:133] op_sel_hi:[1,0]
	v_pk_mul_f32 v[140:141], v[42:43], v[132:133] op_sel_hi:[1,0]
	v_pk_mul_f32 v[142:143], v[40:41], v[132:133] op_sel_hi:[1,0]
	v_pk_mul_f32 v[146:147], v[38:39], v[132:133] op_sel_hi:[1,0]
	v_pk_mul_f32 v[148:149], v[36:37], v[132:133] op_sel_hi:[1,0]
	v_pk_mul_f32 v[156:157], v[34:35], v[132:133] op_sel_hi:[1,0]
	v_pk_mul_f32 v[132:133], v[32:33], v[132:133] op_sel_hi:[1,0]
	v_cvt_pk_bf16_f32 v138, v138, v139
	v_cvt_pk_bf16_f32 v139, v136, v137
	v_cvt_pk_bf16_f32 v136, v142, v143
	v_cvt_pk_bf16_f32 v137, v140, v141
	v_mov_b32_e32 v248, v138
	v_mov_b32_e32 v249, v139
	v_mov_b32_e32 v250, v136
	v_mov_b32_e32 v251, v137
	v_cvt_pk_bf16_f32 v136, v148, v149
	v_cvt_pk_bf16_f32 v137, v146, v147
	v_mov_b32_e32 v244, v136
	v_mov_b32_e32 v245, v137
	v_cvt_pk_bf16_f32 v132, v132, v133
	v_cvt_pk_bf16_f32 v133, v156, v157
	v_mov_b32_e32 v246, v132
	v_mov_b32_e32 v247, v133
	v_and_b32_e32 v242, 16, v190
	v_mul_u32_u24_e32 v242, 3, v242
	v_lshrrev_b32_e32 v242, 1, v242
	v_mov_b32_e32 v243, 0
	v_lshl_add_u64 v[240:241], v[134:135], 0, v[242:243]
	v_permlane16_swap_b32 v248, v250
	v_permlane16_swap_b32 v249, v251
	v_permlane16_swap_b32 v244, v246
	v_permlane16_swap_b32 v245, v247
	flat_store_dwordx4 v[240:241], v[248:251]
	flat_store_dwordx4 v[240:241], v[244:247] offset:64
	ds_read_b32 v132, v155 offset:384
	v_or_b32_e32 v134, 0x60, v130
	v_ashrrev_i32_e32 v135, 31, v134
	v_lshlrev_b64 v[134:135], 10, v[134:135]
	v_lshl_add_u64 v[134:135], v[128:129], 0, v[134:135]
	s_waitcnt lgkmcnt(0)
	v_pk_mul_f32 v[136:137], v[30:31], v[132:133] op_sel_hi:[1,0]
	v_pk_mul_f32 v[138:139], v[28:29], v[132:133] op_sel_hi:[1,0]
	v_pk_mul_f32 v[140:141], v[26:27], v[132:133] op_sel_hi:[1,0]
	v_pk_mul_f32 v[142:143], v[24:25], v[132:133] op_sel_hi:[1,0]
	v_pk_mul_f32 v[146:147], v[22:23], v[132:133] op_sel_hi:[1,0]
	v_pk_mul_f32 v[148:149], v[20:21], v[132:133] op_sel_hi:[1,0]
	v_pk_mul_f32 v[156:157], v[18:19], v[132:133] op_sel_hi:[1,0]
	v_pk_mul_f32 v[132:133], v[16:17], v[132:133] op_sel_hi:[1,0]
	v_cvt_pk_bf16_f32 v138, v138, v139
	v_cvt_pk_bf16_f32 v139, v136, v137
	v_cvt_pk_bf16_f32 v136, v142, v143
	v_cvt_pk_bf16_f32 v137, v140, v141
	v_mov_b32_e32 v248, v138
	v_mov_b32_e32 v249, v139
	v_mov_b32_e32 v250, v136
	v_mov_b32_e32 v251, v137
	v_cvt_pk_bf16_f32 v136, v148, v149
	v_cvt_pk_bf16_f32 v137, v146, v147
	v_mov_b32_e32 v244, v136
	v_mov_b32_e32 v245, v137
	v_cvt_pk_bf16_f32 v132, v132, v133
	v_cvt_pk_bf16_f32 v133, v156, v157
	v_mov_b32_e32 v246, v132
	v_mov_b32_e32 v247, v133
	v_and_b32_e32 v242, 16, v190
	v_mul_u32_u24_e32 v242, 3, v242
	v_lshrrev_b32_e32 v242, 1, v242
	v_mov_b32_e32 v243, 0
	v_lshl_add_u64 v[240:241], v[134:135], 0, v[242:243]
	v_permlane16_swap_b32 v248, v250
	v_permlane16_swap_b32 v249, v251
	v_permlane16_swap_b32 v244, v246
	v_permlane16_swap_b32 v245, v247
	flat_store_dwordx4 v[240:241], v[248:251]
	flat_store_dwordx4 v[240:241], v[244:247] offset:64
	ds_read_b32 v132, v155 offset:448
	v_or_b32_e32 v130, 0x70, v130
	v_ashrrev_i32_e32 v131, 31, v130
	v_lshlrev_b64 v[130:131], 10, v[130:131]
	v_lshl_add_u64 v[128:129], v[128:129], 0, v[130:131]
	s_waitcnt lgkmcnt(0)
	v_pk_mul_f32 v[134:135], v[2:3], v[132:133] op_sel_hi:[1,0]
	v_pk_mul_f32 v[136:137], v[0:1], v[132:133] op_sel_hi:[1,0]
	v_cvt_pk_bf16_f32 v131, v134, v135
	v_pk_mul_f32 v[138:139], v[6:7], v[132:133] op_sel_hi:[1,0]
	v_cvt_pk_bf16_f32 v130, v136, v137
	v_pk_mul_f32 v[140:141], v[4:5], v[132:133] op_sel_hi:[1,0]
	v_mov_b32_e32 v248, v130
	v_mov_b32_e32 v249, v131
	v_cvt_pk_bf16_f32 v130, v140, v141
	v_cvt_pk_bf16_f32 v131, v138, v139
	v_pk_mul_f32 v[142:143], v[10:11], v[132:133] op_sel_hi:[1,0]
	v_pk_mul_f32 v[146:147], v[8:9], v[132:133] op_sel_hi:[1,0]
	v_mov_b32_e32 v250, v130
	v_mov_b32_e32 v251, v131
	v_cvt_pk_bf16_f32 v130, v146, v147
	v_cvt_pk_bf16_f32 v131, v142, v143
	v_pk_mul_f32 v[148:149], v[14:15], v[132:133] op_sel_hi:[1,0]
	v_pk_mul_f32 v[132:133], v[12:13], v[132:133] op_sel_hi:[1,0]
	v_mov_b32_e32 v244, v130
	v_mov_b32_e32 v245, v131
	v_cvt_pk_bf16_f32 v130, v132, v133
	v_cvt_pk_bf16_f32 v131, v148, v149
	v_mov_b32_e32 v246, v130
	v_mov_b32_e32 v247, v131
	v_and_b32_e32 v242, 16, v190
	v_mul_u32_u24_e32 v242, 3, v242
	v_lshrrev_b32_e32 v242, 1, v242
	v_mov_b32_e32 v243, 0
	v_lshl_add_u64 v[240:241], v[128:129], 0, v[242:243]
	v_permlane16_swap_b32 v248, v250
	v_permlane16_swap_b32 v249, v251
	v_permlane16_swap_b32 v244, v246
	v_permlane16_swap_b32 v245, v247
	flat_store_dwordx4 v[240:241], v[248:251]
	flat_store_dwordx4 v[240:241], v[244:247] offset:64

.LBB0_451:
	s_andn2_b64 vcc, exec, s[2:3]
	s_cbranch_vccnz .LBB0_453
	v_lshlrev_b32_e32 v131, 2, v159
	v_lshl_or_b32 v131, v160, 9, v131
	v_add_u32_e32 v134, 0x20800, v131
	ds_read_b32 v135, v134
	v_or_b32_e32 v130, s26, v159
	v_lshl_add_u32 v130, v160, 7, v130
	v_ashrrev_i32_e32 v131, 31, v130
	s_waitcnt lgkmcnt(0)
	v_lshlrev_b64 v[132:133], 10, v[130:131]
	v_mul_f32_e32 v131, v124, v135
	v_mul_f32_e32 v136, 0x3d372713, v131
	v_mul_f32_e32 v136, v131, v136
	v_fma_f32 v136, v131, v136, v131
	v_mul_f32_e32 v136, 0x3f4c422a, v136
	v_add_f32_e32 v136, v136, v136
	v_mul_f32_e32 v136, 0xbfb8aa3b, v136
	v_exp_f32_e32 v136, v136
	v_mov_b32_e32 v155, v145
	s_and_b64 s[2:3], s[24:25], exec
	s_mov_b32 s0, 0x71dfa00
	v_add_f32_e32 v136, 1.0, v136
	v_rcp_f32_e32 v136, v136
	v_lshl_add_u64 v[128:129], v[154:155], 1, s[20:21]
	s_cselect_b32 s0, s0, 0xa1dee00
	v_lshl_add_u64 v[128:129], v[128:129], 0, s[0:1]
	v_mul_f32_e32 v131, v131, v136
	v_mul_f32_e32 v136, v120, v135
	v_mul_f32_e32 v137, 0x3d372713, v136
	v_mul_f32_e32 v137, v136, v137
	v_fma_f32 v137, v136, v137, v136
	v_mul_f32_e32 v137, 0x3f4c422a, v137
	v_add_f32_e32 v137, v137, v137
	v_mul_f32_e32 v137, 0xbfb8aa3b, v137
	v_exp_f32_e32 v137, v137
	v_lshlrev_b32_e32 v144, 3, v151
	v_lshl_add_u64 v[128:129], v[128:129], 0, v[144:145]
	v_lshl_add_u64 v[132:133], v[128:129], 0, v[132:133]
	v_add_f32_e32 v137, 1.0, v137
	v_rcp_f32_e32 v137, v137
	s_nop 0
	v_mul_f32_e32 v138, v136, v137
	v_mul_f32_e32 v136, v116, v135
	v_mul_f32_e32 v137, 0x3d372713, v136
	v_mul_f32_e32 v137, v136, v137
	v_fma_f32 v137, v136, v137, v136
	v_mul_f32_e32 v137, 0x3f4c422a, v137
	v_add_f32_e32 v137, v137, v137
	v_mul_f32_e32 v137, 0xbfb8aa3b, v137
	v_exp_f32_e32 v137, v137
	s_nop 0
	v_add_f32_e32 v137, 1.0, v137
	v_rcp_f32_e32 v137, v137
	s_nop 0
	v_mul_f32_e32 v139, v136, v137
	v_mul_f32_e32 v136, v112, v135
	v_mul_f32_e32 v137, 0x3d372713, v136
	v_mul_f32_e32 v137, v136, v137
	v_fma_f32 v137, v136, v137, v136
	v_mul_f32_e32 v137, 0x3f4c422a, v137
	v_add_f32_e32 v137, v137, v137
	v_mul_f32_e32 v137, 0xbfb8aa3b, v137
	v_exp_f32_e32 v137, v137
	s_nop 0
	v_add_f32_e32 v137, 1.0, v137
	v_rcp_f32_e32 v137, v137
	s_nop 0
	v_mul_f32_e32 v140, v136, v137
	v_mul_f32_e32 v136, v125, v135
	v_mul_f32_e32 v137, 0x3d372713, v136
	v_mul_f32_e32 v137, v136, v137
	v_fma_f32 v137, v136, v137, v136
	v_mul_f32_e32 v137, 0x3f4c422a, v137
	v_add_f32_e32 v137, v137, v137
	v_mul_f32_e32 v137, 0xbfb8aa3b, v137
	v_exp_f32_e32 v137, v137
	s_nop 0
	v_add_f32_e32 v137, 1.0, v137
	v_rcp_f32_e32 v137, v137
	s_nop 0
	v_mul_f32_e32 v136, v136, v137
	v_mul_f32_e32 v137, v121, v135
	v_mul_f32_e32 v141, 0x3d372713, v137
	v_mul_f32_e32 v141, v137, v141
	v_fma_f32 v141, v137, v141, v137
	v_mul_f32_e32 v141, 0x3f4c422a, v141
	v_add_f32_e32 v141, v141, v141
	v_mul_f32_e32 v141, 0xbfb8aa3b, v141
	v_exp_f32_e32 v141, v141
	v_cvt_pk_bf16_f32 v136, v131, v136
	s_nop 0
	v_add_f32_e32 v141, 1.0, v141
	v_rcp_f32_e32 v141, v141
	s_nop 0
	v_mul_f32_e32 v141, v137, v141
	v_mul_f32_e32 v137, v117, v135
	v_mul_f32_e32 v142, 0x3d372713, v137
	v_mul_f32_e32 v142, v137, v142
	v_fma_f32 v142, v137, v142, v137
	v_mul_f32_e32 v142, 0x3f4c422a, v142
	v_add_f32_e32 v142, v142, v142
	v_mul_f32_e32 v142, 0xbfb8aa3b, v142
	v_exp_f32_e32 v142, v142
	s_nop 0
	v_add_f32_e32 v142, 1.0, v142
	v_rcp_f32_e32 v142, v142
	s_nop 0
	v_mul_f32_e32 v142, v137, v142
	v_mul_f32_e32 v137, v113, v135
	v_mul_f32_e32 v143, 0x3d372713, v137
	v_mul_f32_e32 v143, v137, v143
	v_fma_f32 v143, v137, v143, v137
	v_mul_f32_e32 v143, 0x3f4c422a, v143
	v_add_f32_e32 v143, v143, v143
	v_mul_f32_e32 v143, 0xbfb8aa3b, v143
	v_exp_f32_e32 v143, v143
	s_nop 0
	v_add_f32_e32 v143, 1.0, v143
	v_rcp_f32_e32 v143, v143
	s_nop 0
	v_mul_f32_e32 v143, v137, v143
	v_mul_f32_e32 v137, v126, v135
	v_mul_f32_e32 v144, 0x3d372713, v137
	v_mul_f32_e32 v144, v137, v144
	v_fma_f32 v144, v137, v144, v137
	v_mul_f32_e32 v144, 0x3f4c422a, v144
	v_add_f32_e32 v144, v144, v144
	v_mul_f32_e32 v144, 0xbfb8aa3b, v144
	v_exp_f32_e32 v144, v144
	s_nop 0
	v_add_f32_e32 v144, 1.0, v144
	v_rcp_f32_e32 v144, v144
	s_nop 0
	v_mul_f32_e32 v137, v137, v144
	v_mul_f32_e32 v144, v122, v135
	v_mul_f32_e32 v146, 0x3d372713, v144
	v_mul_f32_e32 v146, v144, v146
	v_fma_f32 v146, v144, v146, v144
	v_mul_f32_e32 v146, 0x3f4c422a, v146
	v_add_f32_e32 v146, v146, v146
	v_mul_f32_e32 v146, 0xbfb8aa3b, v146
	v_exp_f32_e32 v146, v146
	s_nop 0
	v_add_f32_e32 v146, 1.0, v146
	v_rcp_f32_e32 v146, v146
	s_nop 0
	v_mul_f32_e32 v144, v144, v146
	v_mul_f32_e32 v146, v118, v135
	v_mul_f32_e32 v147, 0x3d372713, v146
	v_mul_f32_e32 v147, v146, v147
	v_fma_f32 v147, v146, v147, v146
	v_mul_f32_e32 v147, 0x3f4c422a, v147
	v_add_f32_e32 v147, v147, v147
	v_mul_f32_e32 v147, 0xbfb8aa3b, v147
	v_exp_f32_e32 v147, v147
	s_nop 0
	v_add_f32_e32 v147, 1.0, v147
	v_rcp_f32_e32 v147, v147
	s_nop 0
	v_mul_f32_e32 v146, v146, v147
	v_mul_f32_e32 v147, v114, v135
	v_mul_f32_e32 v148, 0x3d372713, v147
	v_mul_f32_e32 v148, v147, v148
	v_fma_f32 v148, v147, v148, v147
	v_mul_f32_e32 v148, 0x3f4c422a, v148
	v_add_f32_e32 v148, v148, v148
	v_mul_f32_e32 v148, 0xbfb8aa3b, v148
	v_exp_f32_e32 v148, v148
	s_nop 0
	v_add_f32_e32 v148, 1.0, v148
	v_rcp_f32_e32 v148, v148
	s_nop 0
	v_mul_f32_e32 v147, v147, v148
	v_mul_f32_e32 v148, v127, v135
	v_mul_f32_e32 v149, 0x3d372713, v148
	v_mul_f32_e32 v149, v148, v149
	v_fma_f32 v149, v148, v149, v148
	v_mul_f32_e32 v149, 0x3f4c422a, v149
	v_add_f32_e32 v149, v149, v149
	v_mul_f32_e32 v149, 0xbfb8aa3b, v149
	v_exp_f32_e32 v149, v149
	s_nop 0
	v_add_f32_e32 v149, 1.0, v149
	v_rcp_f32_e32 v149, v149
	s_nop 0
	v_mul_f32_e32 v148, v148, v149
	v_mul_f32_e32 v149, v123, v135
	v_mul_f32_e32 v155, 0x3d372713, v149
	v_mul_f32_e32 v155, v149, v155
	v_fma_f32 v155, v149, v155, v149
	v_mul_f32_e32 v155, 0x3f4c422a, v155
	v_add_f32_e32 v155, v155, v155
	v_mul_f32_e32 v155, 0xbfb8aa3b, v155
	v_exp_f32_e32 v155, v155
	v_cvt_pk_bf16_f32 v137, v137, v148
	s_waitcnt vmcnt(0)
	v_mov_b32_e32 v248, v136
	v_mov_b32_e32 v249, v137
	v_cvt_pk_bf16_f32 v136, v138, v141
	v_add_f32_e32 v155, 1.0, v155
	v_rcp_f32_e32 v155, v155
	s_nop 0
	v_mul_f32_e32 v149, v149, v155
	v_mul_f32_e32 v155, v119, v135
	v_mul_f32_e32 v156, 0x3d372713, v155
	v_mul_f32_e32 v156, v155, v156
	v_fma_f32 v156, v155, v156, v155
	v_mul_f32_e32 v156, 0x3f4c422a, v156
	v_add_f32_e32 v156, v156, v156
	v_mul_f32_e32 v156, 0xbfb8aa3b, v156
	v_exp_f32_e32 v156, v156
	v_mul_f32_e32 v135, v115, v135
	v_cvt_pk_bf16_f32 v137, v144, v149
	v_mov_b32_e32 v250, v136
	v_mov_b32_e32 v251, v137
	v_add_f32_e32 v156, 1.0, v156
	v_rcp_f32_e32 v156, v156
	v_cvt_pk_bf16_f32 v136, v139, v142
	s_nop 0
	v_mul_f32_e32 v155, v155, v156
	v_mul_f32_e32 v156, 0x3d372713, v135
	v_mul_f32_e32 v156, v135, v156
	v_fma_f32 v156, v135, v156, v135
	v_mul_f32_e32 v156, 0x3f4c422a, v156
	v_add_f32_e32 v156, v156, v156
	v_mul_f32_e32 v156, 0xbfb8aa3b, v156
	v_exp_f32_e32 v156, v156
	v_cvt_pk_bf16_f32 v137, v146, v155
	v_mov_b32_e32 v244, v136
	v_mov_b32_e32 v245, v137
	v_cvt_pk_bf16_f32 v136, v140, v143
	v_add_f32_e32 v156, 1.0, v156
	v_rcp_f32_e32 v156, v156
	s_nop 0
	v_mul_f32_e32 v135, v135, v156
	v_cvt_pk_bf16_f32 v137, v147, v135
	v_mov_b32_e32 v246, v136
	v_mov_b32_e32 v247, v137
	v_and_b32_e32 v242, 16, v190
	v_mul_u32_u24_e32 v242, 3, v242
	v_lshrrev_b32_e32 v242, 1, v242
	v_mov_b32_e32 v243, 0
	v_lshl_add_u64 v[240:241], v[132:133], 0, v[242:243]
	v_permlane16_swap_b32 v248, v250
	v_permlane16_swap_b32 v249, v251
	v_permlane16_swap_b32 v244, v246
	v_permlane16_swap_b32 v245, v247
	flat_store_dwordx4 v[240:241], v[248:251]
	flat_store_dwordx4 v[240:241], v[244:247] offset:64
	ds_read_b32 v131, v134 offset:64
	v_or_b32_e32 v132, 16, v130
	v_ashrrev_i32_e32 v133, 31, v132
	v_lshlrev_b64 v[132:133], 10, v[132:133]
	v_lshl_add_u64 v[132:133], v[128:129], 0, v[132:133]
	s_waitcnt lgkmcnt(0)
	v_mul_f32_e32 v135, v108, v131
	v_mul_f32_e32 v136, 0x3d372713, v135
	v_mul_f32_e32 v136, v135, v136
	v_fma_f32 v136, v135, v136, v135
	v_mul_f32_e32 v136, 0x3f4c422a, v136
	v_add_f32_e32 v136, v136, v136
	v_mul_f32_e32 v136, 0xbfb8aa3b, v136
	v_exp_f32_e32 v136, v136
	s_nop 0
	v_add_f32_e32 v136, 1.0, v136
	v_rcp_f32_e32 v136, v136
	s_nop 0
	v_mul_f32_e32 v135, v135, v136
	v_mul_f32_e32 v136, v104, v131
	v_mul_f32_e32 v137, 0x3d372713, v136
	v_mul_f32_e32 v137, v136, v137
	v_fma_f32 v137, v136, v137, v136
	v_mul_f32_e32 v137, 0x3f4c422a, v137
	v_add_f32_e32 v137, v137, v137
	v_mul_f32_e32 v137, 0xbfb8aa3b, v137
	v_exp_f32_e32 v137, v137
	s_nop 0
	v_add_f32_e32 v137, 1.0, v137
	v_rcp_f32_e32 v137, v137
	s_nop 0
	v_mul_f32_e32 v138, v136, v137
	v_mul_f32_e32 v136, v100, v131
	v_mul_f32_e32 v137, 0x3d372713, v136
	v_mul_f32_e32 v137, v136, v137
	v_fma_f32 v137, v136, v137, v136
	v_mul_f32_e32 v137, 0x3f4c422a, v137
	v_add_f32_e32 v137, v137, v137
	v_mul_f32_e32 v137, 0xbfb8aa3b, v137
	v_exp_f32_e32 v137, v137
	s_nop 0
	v_add_f32_e32 v137, 1.0, v137
	v_rcp_f32_e32 v137, v137
	s_nop 0
	v_mul_f32_e32 v139, v136, v137
	v_mul_f32_e32 v136, v96, v131
	v_mul_f32_e32 v137, 0x3d372713, v136
	v_mul_f32_e32 v137, v136, v137
	v_fma_f32 v137, v136, v137, v136
	v_mul_f32_e32 v137, 0x3f4c422a, v137
	v_add_f32_e32 v137, v137, v137
	v_mul_f32_e32 v137, 0xbfb8aa3b, v137
	v_exp_f32_e32 v137, v137
	s_nop 0
	v_add_f32_e32 v137, 1.0, v137
	v_rcp_f32_e32 v137, v137
	s_nop 0
	v_mul_f32_e32 v140, v136, v137
	v_mul_f32_e32 v136, v109, v131
	v_mul_f32_e32 v137, 0x3d372713, v136
	v_mul_f32_e32 v137, v136, v137
	v_fma_f32 v137, v136, v137, v136
	v_mul_f32_e32 v137, 0x3f4c422a, v137
	v_add_f32_e32 v137, v137, v137
	v_mul_f32_e32 v137, 0xbfb8aa3b, v137
	v_exp_f32_e32 v137, v137
	s_nop 0
	v_add_f32_e32 v137, 1.0, v137
	v_rcp_f32_e32 v137, v137
	s_nop 0
	v_mul_f32_e32 v136, v136, v137
	v_mul_f32_e32 v137, v105, v131
	v_mul_f32_e32 v141, 0x3d372713, v137
	v_mul_f32_e32 v141, v137, v141
	v_fma_f32 v141, v137, v141, v137
	v_mul_f32_e32 v141, 0x3f4c422a, v141
	v_add_f32_e32 v141, v141, v141
	v_mul_f32_e32 v141, 0xbfb8aa3b, v141
	v_exp_f32_e32 v141, v141
	v_cvt_pk_bf16_f32 v136, v135, v136
	s_nop 0
	v_add_f32_e32 v141, 1.0, v141
	v_rcp_f32_e32 v141, v141
	s_nop 0
	v_mul_f32_e32 v141, v137, v141
	v_mul_f32_e32 v137, v101, v131
	v_mul_f32_e32 v142, 0x3d372713, v137
	v_mul_f32_e32 v142, v137, v142
	v_fma_f32 v142, v137, v142, v137
	v_mul_f32_e32 v142, 0x3f4c422a, v142
	v_add_f32_e32 v142, v142, v142
	v_mul_f32_e32 v142, 0xbfb8aa3b, v142
	v_exp_f32_e32 v142, v142
	s_nop 0
	v_add_f32_e32 v142, 1.0, v142
	v_rcp_f32_e32 v142, v142
	s_nop 0
	v_mul_f32_e32 v142, v137, v142
	v_mul_f32_e32 v137, v97, v131
	v_mul_f32_e32 v143, 0x3d372713, v137
	v_mul_f32_e32 v143, v137, v143
	v_fma_f32 v143, v137, v143, v137
	v_mul_f32_e32 v143, 0x3f4c422a, v143
	v_add_f32_e32 v143, v143, v143
	v_mul_f32_e32 v143, 0xbfb8aa3b, v143
	v_exp_f32_e32 v143, v143
	s_nop 0
	v_add_f32_e32 v143, 1.0, v143
	v_rcp_f32_e32 v143, v143
	s_nop 0
	v_mul_f32_e32 v143, v137, v143
	v_mul_f32_e32 v137, v110, v131
	v_mul_f32_e32 v144, 0x3d372713, v137
	v_mul_f32_e32 v144, v137, v144
	v_fma_f32 v144, v137, v144, v137
	v_mul_f32_e32 v144, 0x3f4c422a, v144
	v_add_f32_e32 v144, v144, v144
	v_mul_f32_e32 v144, 0xbfb8aa3b, v144
	v_exp_f32_e32 v144, v144
	s_nop 0
	v_add_f32_e32 v144, 1.0, v144
	v_rcp_f32_e32 v144, v144
	s_nop 0
	v_mul_f32_e32 v137, v137, v144
	v_mul_f32_e32 v144, v106, v131
	v_mul_f32_e32 v146, 0x3d372713, v144
	v_mul_f32_e32 v146, v144, v146
	v_fma_f32 v146, v144, v146, v144
	v_mul_f32_e32 v146, 0x3f4c422a, v146
	v_add_f32_e32 v146, v146, v146
	v_mul_f32_e32 v146, 0xbfb8aa3b, v146
	v_exp_f32_e32 v146, v146
	s_nop 0
	v_add_f32_e32 v146, 1.0, v146
	v_rcp_f32_e32 v146, v146
	s_nop 0
	v_mul_f32_e32 v144, v144, v146
	v_mul_f32_e32 v146, v102, v131
	v_mul_f32_e32 v147, 0x3d372713, v146
	v_mul_f32_e32 v147, v146, v147
	v_fma_f32 v147, v146, v147, v146
	v_mul_f32_e32 v147, 0x3f4c422a, v147
	v_add_f32_e32 v147, v147, v147
	v_mul_f32_e32 v147, 0xbfb8aa3b, v147
	v_exp_f32_e32 v147, v147
	s_nop 0
	v_add_f32_e32 v147, 1.0, v147
	v_rcp_f32_e32 v147, v147
	s_nop 0
	v_mul_f32_e32 v146, v146, v147
	v_mul_f32_e32 v147, v98, v131
	v_mul_f32_e32 v148, 0x3d372713, v147
	v_mul_f32_e32 v148, v147, v148
	v_fma_f32 v148, v147, v148, v147
	v_mul_f32_e32 v148, 0x3f4c422a, v148
	v_add_f32_e32 v148, v148, v148
	v_mul_f32_e32 v148, 0xbfb8aa3b, v148
	v_exp_f32_e32 v148, v148
	s_nop 0
	v_add_f32_e32 v148, 1.0, v148
	v_rcp_f32_e32 v148, v148
	s_nop 0
	v_mul_f32_e32 v147, v147, v148
	v_mul_f32_e32 v148, v111, v131
	v_mul_f32_e32 v149, 0x3d372713, v148
	v_mul_f32_e32 v149, v148, v149
	v_fma_f32 v149, v148, v149, v148
	v_mul_f32_e32 v149, 0x3f4c422a, v149
	v_add_f32_e32 v149, v149, v149
	v_mul_f32_e32 v149, 0xbfb8aa3b, v149
	v_exp_f32_e32 v149, v149
	s_nop 0
	v_add_f32_e32 v149, 1.0, v149
	v_rcp_f32_e32 v149, v149
	s_nop 0
	v_mul_f32_e32 v148, v148, v149
	v_mul_f32_e32 v149, v107, v131
	v_mul_f32_e32 v155, 0x3d372713, v149
	v_mul_f32_e32 v155, v149, v155
	v_fma_f32 v155, v149, v155, v149
	v_mul_f32_e32 v155, 0x3f4c422a, v155
	v_add_f32_e32 v155, v155, v155
	v_mul_f32_e32 v155, 0xbfb8aa3b, v155
	v_exp_f32_e32 v155, v155
	v_cvt_pk_bf16_f32 v137, v137, v148
	v_mov_b32_e32 v248, v136
	v_mov_b32_e32 v249, v137
	v_cvt_pk_bf16_f32 v136, v138, v141
	v_add_f32_e32 v155, 1.0, v155
	v_rcp_f32_e32 v155, v155
	s_nop 0
	v_mul_f32_e32 v149, v149, v155
	v_mul_f32_e32 v155, v103, v131
	v_mul_f32_e32 v156, 0x3d372713, v155
	v_mul_f32_e32 v156, v155, v156
	v_fma_f32 v156, v155, v156, v155
	v_mul_f32_e32 v156, 0x3f4c422a, v156
	v_add_f32_e32 v156, v156, v156
	v_mul_f32_e32 v156, 0xbfb8aa3b, v156
	v_exp_f32_e32 v156, v156
	v_mul_f32_e32 v131, v99, v131
	v_cvt_pk_bf16_f32 v137, v144, v149
	v_mov_b32_e32 v250, v136
	v_mov_b32_e32 v251, v137
	v_add_f32_e32 v156, 1.0, v156
	v_rcp_f32_e32 v156, v156
	v_cvt_pk_bf16_f32 v136, v139, v142
	s_nop 0
	v_mul_f32_e32 v155, v155, v156
	v_mul_f32_e32 v156, 0x3d372713, v131
	v_mul_f32_e32 v156, v131, v156
	v_fma_f32 v156, v131, v156, v131
	v_mul_f32_e32 v156, 0x3f4c422a, v156
	v_add_f32_e32 v156, v156, v156
	v_mul_f32_e32 v156, 0xbfb8aa3b, v156
	v_exp_f32_e32 v156, v156
	v_cvt_pk_bf16_f32 v137, v146, v155
	v_mov_b32_e32 v244, v136
	v_mov_b32_e32 v245, v137
	v_cvt_pk_bf16_f32 v136, v140, v143
	v_add_f32_e32 v156, 1.0, v156
	v_rcp_f32_e32 v156, v156
	s_nop 0
	v_mul_f32_e32 v131, v131, v156
	v_cvt_pk_bf16_f32 v137, v147, v131
	v_mov_b32_e32 v246, v136
	v_mov_b32_e32 v247, v137
	v_and_b32_e32 v242, 16, v190
	v_mul_u32_u24_e32 v242, 3, v242
	v_lshrrev_b32_e32 v242, 1, v242
	v_mov_b32_e32 v243, 0
	v_lshl_add_u64 v[240:241], v[132:133], 0, v[242:243]
	v_permlane16_swap_b32 v248, v250
	v_permlane16_swap_b32 v249, v251
	v_permlane16_swap_b32 v244, v246
	v_permlane16_swap_b32 v245, v247
	flat_store_dwordx4 v[240:241], v[248:251]
	flat_store_dwordx4 v[240:241], v[244:247] offset:64
	ds_read_b32 v131, v134 offset:128
	v_or_b32_e32 v132, 32, v130
	v_ashrrev_i32_e32 v133, 31, v132
	v_lshlrev_b64 v[132:133], 10, v[132:133]
	v_lshl_add_u64 v[132:133], v[128:129], 0, v[132:133]
	s_waitcnt lgkmcnt(0)
	v_mul_f32_e32 v135, v92, v131
	v_mul_f32_e32 v136, 0x3d372713, v135
	v_mul_f32_e32 v136, v135, v136
	v_fma_f32 v136, v135, v136, v135
	v_mul_f32_e32 v136, 0x3f4c422a, v136
	v_add_f32_e32 v136, v136, v136
	v_mul_f32_e32 v136, 0xbfb8aa3b, v136
	v_exp_f32_e32 v136, v136
	s_nop 0
	v_add_f32_e32 v136, 1.0, v136
	v_rcp_f32_e32 v136, v136
	s_nop 0
	v_mul_f32_e32 v135, v135, v136
	v_mul_f32_e32 v136, v88, v131
	v_mul_f32_e32 v137, 0x3d372713, v136
	v_mul_f32_e32 v137, v136, v137
	v_fma_f32 v137, v136, v137, v136
	v_mul_f32_e32 v137, 0x3f4c422a, v137
	v_add_f32_e32 v137, v137, v137
	v_mul_f32_e32 v137, 0xbfb8aa3b, v137
	v_exp_f32_e32 v137, v137
	s_nop 0
	v_add_f32_e32 v137, 1.0, v137
	v_rcp_f32_e32 v137, v137
	s_nop 0
	v_mul_f32_e32 v138, v136, v137
	v_mul_f32_e32 v136, v84, v131
	v_mul_f32_e32 v137, 0x3d372713, v136
	v_mul_f32_e32 v137, v136, v137
	v_fma_f32 v137, v136, v137, v136
	v_mul_f32_e32 v137, 0x3f4c422a, v137
	v_add_f32_e32 v137, v137, v137
	v_mul_f32_e32 v137, 0xbfb8aa3b, v137
	v_exp_f32_e32 v137, v137
	s_nop 0
	v_add_f32_e32 v137, 1.0, v137
	v_rcp_f32_e32 v137, v137
	s_nop 0
	v_mul_f32_e32 v139, v136, v137
	v_mul_f32_e32 v136, v80, v131
	v_mul_f32_e32 v137, 0x3d372713, v136
	v_mul_f32_e32 v137, v136, v137
	v_fma_f32 v137, v136, v137, v136
	v_mul_f32_e32 v137, 0x3f4c422a, v137
	v_add_f32_e32 v137, v137, v137
	v_mul_f32_e32 v137, 0xbfb8aa3b, v137
	v_exp_f32_e32 v137, v137
	s_nop 0
	v_add_f32_e32 v137, 1.0, v137
	v_rcp_f32_e32 v137, v137
	s_nop 0
	v_mul_f32_e32 v140, v136, v137
	v_mul_f32_e32 v136, v93, v131
	v_mul_f32_e32 v137, 0x3d372713, v136
	v_mul_f32_e32 v137, v136, v137
	v_fma_f32 v137, v136, v137, v136
	v_mul_f32_e32 v137, 0x3f4c422a, v137
	v_add_f32_e32 v137, v137, v137
	v_mul_f32_e32 v137, 0xbfb8aa3b, v137
	v_exp_f32_e32 v137, v137
	s_nop 0
	v_add_f32_e32 v137, 1.0, v137
	v_rcp_f32_e32 v137, v137
	s_nop 0
	v_mul_f32_e32 v136, v136, v137
	v_mul_f32_e32 v137, v89, v131
	v_mul_f32_e32 v141, 0x3d372713, v137
	v_mul_f32_e32 v141, v137, v141
	v_fma_f32 v141, v137, v141, v137
	v_mul_f32_e32 v141, 0x3f4c422a, v141
	v_add_f32_e32 v141, v141, v141
	v_mul_f32_e32 v141, 0xbfb8aa3b, v141
	v_exp_f32_e32 v141, v141
	v_cvt_pk_bf16_f32 v136, v135, v136
	s_nop 0
	v_add_f32_e32 v141, 1.0, v141
	v_rcp_f32_e32 v141, v141
	s_nop 0
	v_mul_f32_e32 v141, v137, v141
	v_mul_f32_e32 v137, v85, v131
	v_mul_f32_e32 v142, 0x3d372713, v137
	v_mul_f32_e32 v142, v137, v142
	v_fma_f32 v142, v137, v142, v137
	v_mul_f32_e32 v142, 0x3f4c422a, v142
	v_add_f32_e32 v142, v142, v142
	v_mul_f32_e32 v142, 0xbfb8aa3b, v142
	v_exp_f32_e32 v142, v142
	s_nop 0
	v_add_f32_e32 v142, 1.0, v142
	v_rcp_f32_e32 v142, v142
	s_nop 0
	v_mul_f32_e32 v142, v137, v142
	v_mul_f32_e32 v137, v81, v131
	v_mul_f32_e32 v143, 0x3d372713, v137
	v_mul_f32_e32 v143, v137, v143
	v_fma_f32 v143, v137, v143, v137
	v_mul_f32_e32 v143, 0x3f4c422a, v143
	v_add_f32_e32 v143, v143, v143
	v_mul_f32_e32 v143, 0xbfb8aa3b, v143
	v_exp_f32_e32 v143, v143
	s_nop 0
	v_add_f32_e32 v143, 1.0, v143
	v_rcp_f32_e32 v143, v143
	s_nop 0
	v_mul_f32_e32 v143, v137, v143
	v_mul_f32_e32 v137, v94, v131
	v_mul_f32_e32 v144, 0x3d372713, v137
	v_mul_f32_e32 v144, v137, v144
	v_fma_f32 v144, v137, v144, v137
	v_mul_f32_e32 v144, 0x3f4c422a, v144
	v_add_f32_e32 v144, v144, v144
	v_mul_f32_e32 v144, 0xbfb8aa3b, v144
	v_exp_f32_e32 v144, v144
	s_nop 0
	v_add_f32_e32 v144, 1.0, v144
	v_rcp_f32_e32 v144, v144
	s_nop 0
	v_mul_f32_e32 v137, v137, v144
	v_mul_f32_e32 v144, v90, v131
	v_mul_f32_e32 v146, 0x3d372713, v144
	v_mul_f32_e32 v146, v144, v146
	v_fma_f32 v146, v144, v146, v144
	v_mul_f32_e32 v146, 0x3f4c422a, v146
	v_add_f32_e32 v146, v146, v146
	v_mul_f32_e32 v146, 0xbfb8aa3b, v146
	v_exp_f32_e32 v146, v146
	s_nop 0
	v_add_f32_e32 v146, 1.0, v146
	v_rcp_f32_e32 v146, v146
	s_nop 0
	v_mul_f32_e32 v144, v144, v146
	v_mul_f32_e32 v146, v86, v131
	v_mul_f32_e32 v147, 0x3d372713, v146
	v_mul_f32_e32 v147, v146, v147
	v_fma_f32 v147, v146, v147, v146
	v_mul_f32_e32 v147, 0x3f4c422a, v147
	v_add_f32_e32 v147, v147, v147
	v_mul_f32_e32 v147, 0xbfb8aa3b, v147
	v_exp_f32_e32 v147, v147
	s_nop 0
	v_add_f32_e32 v147, 1.0, v147
	v_rcp_f32_e32 v147, v147
	s_nop 0
	v_mul_f32_e32 v146, v146, v147
	v_mul_f32_e32 v147, v82, v131
	v_mul_f32_e32 v148, 0x3d372713, v147
	v_mul_f32_e32 v148, v147, v148
	v_fma_f32 v148, v147, v148, v147
	v_mul_f32_e32 v148, 0x3f4c422a, v148
	v_add_f32_e32 v148, v148, v148
	v_mul_f32_e32 v148, 0xbfb8aa3b, v148
	v_exp_f32_e32 v148, v148
	s_nop 0
	v_add_f32_e32 v148, 1.0, v148
	v_rcp_f32_e32 v148, v148
	s_nop 0
	v_mul_f32_e32 v147, v147, v148
	v_mul_f32_e32 v148, v95, v131
	v_mul_f32_e32 v149, 0x3d372713, v148
	v_mul_f32_e32 v149, v148, v149
	v_fma_f32 v149, v148, v149, v148
	v_mul_f32_e32 v149, 0x3f4c422a, v149
	v_add_f32_e32 v149, v149, v149
	v_mul_f32_e32 v149, 0xbfb8aa3b, v149
	v_exp_f32_e32 v149, v149
	s_nop 0
	v_add_f32_e32 v149, 1.0, v149
	v_rcp_f32_e32 v149, v149
	s_nop 0
	v_mul_f32_e32 v148, v148, v149
	v_mul_f32_e32 v149, v91, v131
	v_mul_f32_e32 v155, 0x3d372713, v149
	v_mul_f32_e32 v155, v149, v155
	v_fma_f32 v155, v149, v155, v149
	v_mul_f32_e32 v155, 0x3f4c422a, v155
	v_add_f32_e32 v155, v155, v155
	v_mul_f32_e32 v155, 0xbfb8aa3b, v155
	v_exp_f32_e32 v155, v155
	v_cvt_pk_bf16_f32 v137, v137, v148
	v_mov_b32_e32 v248, v136
	v_mov_b32_e32 v249, v137
	v_cvt_pk_bf16_f32 v136, v138, v141
	v_add_f32_e32 v155, 1.0, v155
	v_rcp_f32_e32 v155, v155
	s_nop 0
	v_mul_f32_e32 v149, v149, v155
	v_mul_f32_e32 v155, v87, v131
	v_mul_f32_e32 v156, 0x3d372713, v155
	v_mul_f32_e32 v156, v155, v156
	v_fma_f32 v156, v155, v156, v155
	v_mul_f32_e32 v156, 0x3f4c422a, v156
	v_add_f32_e32 v156, v156, v156
	v_mul_f32_e32 v156, 0xbfb8aa3b, v156
	v_exp_f32_e32 v156, v156
	v_mul_f32_e32 v131, v83, v131
	v_cvt_pk_bf16_f32 v137, v144, v149
	v_mov_b32_e32 v250, v136
	v_mov_b32_e32 v251, v137
	v_add_f32_e32 v156, 1.0, v156
	v_rcp_f32_e32 v156, v156
	v_cvt_pk_bf16_f32 v136, v139, v142
	s_nop 0
	v_mul_f32_e32 v155, v155, v156
	v_mul_f32_e32 v156, 0x3d372713, v131
	v_mul_f32_e32 v156, v131, v156
	v_fma_f32 v156, v131, v156, v131
	v_mul_f32_e32 v156, 0x3f4c422a, v156
	v_add_f32_e32 v156, v156, v156
	v_mul_f32_e32 v156, 0xbfb8aa3b, v156
	v_exp_f32_e32 v156, v156
	v_cvt_pk_bf16_f32 v137, v146, v155
	v_mov_b32_e32 v244, v136
	v_mov_b32_e32 v245, v137
	v_cvt_pk_bf16_f32 v136, v140, v143
	v_add_f32_e32 v156, 1.0, v156
	v_rcp_f32_e32 v156, v156
	s_nop 0
	v_mul_f32_e32 v131, v131, v156
	v_cvt_pk_bf16_f32 v137, v147, v131
	v_mov_b32_e32 v246, v136
	v_mov_b32_e32 v247, v137
	v_and_b32_e32 v242, 16, v190
	v_mul_u32_u24_e32 v242, 3, v242
	v_lshrrev_b32_e32 v242, 1, v242
	v_mov_b32_e32 v243, 0
	v_lshl_add_u64 v[240:241], v[132:133], 0, v[242:243]
	v_permlane16_swap_b32 v248, v250
	v_permlane16_swap_b32 v249, v251
	v_permlane16_swap_b32 v244, v246
	v_permlane16_swap_b32 v245, v247
	flat_store_dwordx4 v[240:241], v[248:251]
	flat_store_dwordx4 v[240:241], v[244:247] offset:64
	ds_read_b32 v131, v134 offset:192
	v_or_b32_e32 v132, 48, v130
	v_ashrrev_i32_e32 v133, 31, v132
	v_lshlrev_b64 v[132:133], 10, v[132:133]
	v_lshl_add_u64 v[132:133], v[128:129], 0, v[132:133]
	s_waitcnt lgkmcnt(0)
	v_mul_f32_e32 v135, v76, v131
	v_mul_f32_e32 v136, 0x3d372713, v135
	v_mul_f32_e32 v136, v135, v136
	v_fma_f32 v136, v135, v136, v135
	v_mul_f32_e32 v136, 0x3f4c422a, v136
	v_add_f32_e32 v136, v136, v136
	v_mul_f32_e32 v136, 0xbfb8aa3b, v136
	v_exp_f32_e32 v136, v136
	s_nop 0
	v_add_f32_e32 v136, 1.0, v136
	v_rcp_f32_e32 v136, v136
	s_nop 0
	v_mul_f32_e32 v135, v135, v136
	v_mul_f32_e32 v136, v72, v131
	v_mul_f32_e32 v137, 0x3d372713, v136
	v_mul_f32_e32 v137, v136, v137
	v_fma_f32 v137, v136, v137, v136
	v_mul_f32_e32 v137, 0x3f4c422a, v137
	v_add_f32_e32 v137, v137, v137
	v_mul_f32_e32 v137, 0xbfb8aa3b, v137
	v_exp_f32_e32 v137, v137
	s_nop 0
	v_add_f32_e32 v137, 1.0, v137
	v_rcp_f32_e32 v137, v137
	s_nop 0
	v_mul_f32_e32 v138, v136, v137
	v_mul_f32_e32 v136, v68, v131
	v_mul_f32_e32 v137, 0x3d372713, v136
	v_mul_f32_e32 v137, v136, v137
	v_fma_f32 v137, v136, v137, v136
	v_mul_f32_e32 v137, 0x3f4c422a, v137
	v_add_f32_e32 v137, v137, v137
	v_mul_f32_e32 v137, 0xbfb8aa3b, v137
	v_exp_f32_e32 v137, v137
	s_nop 0
	v_add_f32_e32 v137, 1.0, v137
	v_rcp_f32_e32 v137, v137
	s_nop 0
	v_mul_f32_e32 v139, v136, v137
	v_mul_f32_e32 v136, v64, v131
	v_mul_f32_e32 v137, 0x3d372713, v136
	v_mul_f32_e32 v137, v136, v137
	v_fma_f32 v137, v136, v137, v136
	v_mul_f32_e32 v137, 0x3f4c422a, v137
	v_add_f32_e32 v137, v137, v137
	v_mul_f32_e32 v137, 0xbfb8aa3b, v137
	v_exp_f32_e32 v137, v137
	s_nop 0
	v_add_f32_e32 v137, 1.0, v137
	v_rcp_f32_e32 v137, v137
	s_nop 0
	v_mul_f32_e32 v140, v136, v137
	v_mul_f32_e32 v136, v77, v131
	v_mul_f32_e32 v137, 0x3d372713, v136
	v_mul_f32_e32 v137, v136, v137
	v_fma_f32 v137, v136, v137, v136
	v_mul_f32_e32 v137, 0x3f4c422a, v137
	v_add_f32_e32 v137, v137, v137
	v_mul_f32_e32 v137, 0xbfb8aa3b, v137
	v_exp_f32_e32 v137, v137
	s_nop 0
	v_add_f32_e32 v137, 1.0, v137
	v_rcp_f32_e32 v137, v137
	s_nop 0
	v_mul_f32_e32 v136, v136, v137
	v_mul_f32_e32 v137, v73, v131
	v_mul_f32_e32 v141, 0x3d372713, v137
	v_mul_f32_e32 v141, v137, v141
	v_fma_f32 v141, v137, v141, v137
	v_mul_f32_e32 v141, 0x3f4c422a, v141
	v_add_f32_e32 v141, v141, v141
	v_mul_f32_e32 v141, 0xbfb8aa3b, v141
	v_exp_f32_e32 v141, v141
	v_cvt_pk_bf16_f32 v136, v135, v136
	s_nop 0
	v_add_f32_e32 v141, 1.0, v141
	v_rcp_f32_e32 v141, v141
	s_nop 0
	v_mul_f32_e32 v141, v137, v141
	v_mul_f32_e32 v137, v69, v131
	v_mul_f32_e32 v142, 0x3d372713, v137
	v_mul_f32_e32 v142, v137, v142
	v_fma_f32 v142, v137, v142, v137
	v_mul_f32_e32 v142, 0x3f4c422a, v142
	v_add_f32_e32 v142, v142, v142
	v_mul_f32_e32 v142, 0xbfb8aa3b, v142
	v_exp_f32_e32 v142, v142
	s_nop 0
	v_add_f32_e32 v142, 1.0, v142
	v_rcp_f32_e32 v142, v142
	s_nop 0
	v_mul_f32_e32 v142, v137, v142
	v_mul_f32_e32 v137, v65, v131
	v_mul_f32_e32 v143, 0x3d372713, v137
	v_mul_f32_e32 v143, v137, v143
	v_fma_f32 v143, v137, v143, v137
	v_mul_f32_e32 v143, 0x3f4c422a, v143
	v_add_f32_e32 v143, v143, v143
	v_mul_f32_e32 v143, 0xbfb8aa3b, v143
	v_exp_f32_e32 v143, v143
	s_nop 0
	v_add_f32_e32 v143, 1.0, v143
	v_rcp_f32_e32 v143, v143
	s_nop 0
	v_mul_f32_e32 v143, v137, v143
	v_mul_f32_e32 v137, v78, v131
	v_mul_f32_e32 v144, 0x3d372713, v137
	v_mul_f32_e32 v144, v137, v144
	v_fma_f32 v144, v137, v144, v137
	v_mul_f32_e32 v144, 0x3f4c422a, v144
	v_add_f32_e32 v144, v144, v144
	v_mul_f32_e32 v144, 0xbfb8aa3b, v144
	v_exp_f32_e32 v144, v144
	s_nop 0
	v_add_f32_e32 v144, 1.0, v144
	v_rcp_f32_e32 v144, v144
	s_nop 0
	v_mul_f32_e32 v137, v137, v144
	v_mul_f32_e32 v144, v74, v131
	v_mul_f32_e32 v146, 0x3d372713, v144
	v_mul_f32_e32 v146, v144, v146
	v_fma_f32 v146, v144, v146, v144
	v_mul_f32_e32 v146, 0x3f4c422a, v146
	v_add_f32_e32 v146, v146, v146
	v_mul_f32_e32 v146, 0xbfb8aa3b, v146
	v_exp_f32_e32 v146, v146
	s_nop 0
	v_add_f32_e32 v146, 1.0, v146
	v_rcp_f32_e32 v146, v146
	s_nop 0
	v_mul_f32_e32 v144, v144, v146
	v_mul_f32_e32 v146, v70, v131
	v_mul_f32_e32 v147, 0x3d372713, v146
	v_mul_f32_e32 v147, v146, v147
	v_fma_f32 v147, v146, v147, v146
	v_mul_f32_e32 v147, 0x3f4c422a, v147
	v_add_f32_e32 v147, v147, v147
	v_mul_f32_e32 v147, 0xbfb8aa3b, v147
	v_exp_f32_e32 v147, v147
	s_nop 0
	v_add_f32_e32 v147, 1.0, v147
	v_rcp_f32_e32 v147, v147
	s_nop 0
	v_mul_f32_e32 v146, v146, v147
	v_mul_f32_e32 v147, v66, v131
	v_mul_f32_e32 v148, 0x3d372713, v147
	v_mul_f32_e32 v148, v147, v148
	v_fma_f32 v148, v147, v148, v147
	v_mul_f32_e32 v148, 0x3f4c422a, v148
	v_add_f32_e32 v148, v148, v148
	v_mul_f32_e32 v148, 0xbfb8aa3b, v148
	v_exp_f32_e32 v148, v148
	s_nop 0
	v_add_f32_e32 v148, 1.0, v148
	v_rcp_f32_e32 v148, v148
	s_nop 0
	v_mul_f32_e32 v147, v147, v148
	v_mul_f32_e32 v148, v79, v131
	v_mul_f32_e32 v149, 0x3d372713, v148
	v_mul_f32_e32 v149, v148, v149
	v_fma_f32 v149, v148, v149, v148
	v_mul_f32_e32 v149, 0x3f4c422a, v149
	v_add_f32_e32 v149, v149, v149
	v_mul_f32_e32 v149, 0xbfb8aa3b, v149
	v_exp_f32_e32 v149, v149
	s_nop 0
	v_add_f32_e32 v149, 1.0, v149
	v_rcp_f32_e32 v149, v149
	s_nop 0
	v_mul_f32_e32 v148, v148, v149
	v_mul_f32_e32 v149, v75, v131
	v_mul_f32_e32 v155, 0x3d372713, v149
	v_mul_f32_e32 v155, v149, v155
	v_fma_f32 v155, v149, v155, v149
	v_mul_f32_e32 v155, 0x3f4c422a, v155
	v_add_f32_e32 v155, v155, v155
	v_mul_f32_e32 v155, 0xbfb8aa3b, v155
	v_exp_f32_e32 v155, v155
	v_cvt_pk_bf16_f32 v137, v137, v148
	v_mov_b32_e32 v248, v136
	v_mov_b32_e32 v249, v137
	v_cvt_pk_bf16_f32 v136, v138, v141
	v_add_f32_e32 v155, 1.0, v155
	v_rcp_f32_e32 v155, v155
	s_nop 0
	v_mul_f32_e32 v149, v149, v155
	v_mul_f32_e32 v155, v71, v131
	v_mul_f32_e32 v156, 0x3d372713, v155
	v_mul_f32_e32 v156, v155, v156
	v_fma_f32 v156, v155, v156, v155
	v_mul_f32_e32 v156, 0x3f4c422a, v156
	v_add_f32_e32 v156, v156, v156
	v_mul_f32_e32 v156, 0xbfb8aa3b, v156
	v_exp_f32_e32 v156, v156
	v_mul_f32_e32 v131, v67, v131
	v_cvt_pk_bf16_f32 v137, v144, v149
	v_mov_b32_e32 v250, v136
	v_mov_b32_e32 v251, v137
	v_add_f32_e32 v156, 1.0, v156
	v_rcp_f32_e32 v156, v156
	v_cvt_pk_bf16_f32 v136, v139, v142
	s_nop 0
	v_mul_f32_e32 v155, v155, v156
	v_mul_f32_e32 v156, 0x3d372713, v131
	v_mul_f32_e32 v156, v131, v156
	v_fma_f32 v156, v131, v156, v131
	v_mul_f32_e32 v156, 0x3f4c422a, v156
	v_add_f32_e32 v156, v156, v156
	v_mul_f32_e32 v156, 0xbfb8aa3b, v156
	v_exp_f32_e32 v156, v156
	v_cvt_pk_bf16_f32 v137, v146, v155
	v_mov_b32_e32 v244, v136
	v_mov_b32_e32 v245, v137
	v_cvt_pk_bf16_f32 v136, v140, v143
	v_add_f32_e32 v156, 1.0, v156
	v_rcp_f32_e32 v156, v156
	s_nop 0
	v_mul_f32_e32 v131, v131, v156
	v_cvt_pk_bf16_f32 v137, v147, v131
	v_mov_b32_e32 v246, v136
	v_mov_b32_e32 v247, v137
	v_and_b32_e32 v242, 16, v190
	v_mul_u32_u24_e32 v242, 3, v242
	v_lshrrev_b32_e32 v242, 1, v242
	v_mov_b32_e32 v243, 0
	v_lshl_add_u64 v[240:241], v[132:133], 0, v[242:243]
	v_permlane16_swap_b32 v248, v250
	v_permlane16_swap_b32 v249, v251
	v_permlane16_swap_b32 v244, v246
	v_permlane16_swap_b32 v245, v247
	flat_store_dwordx4 v[240:241], v[248:251]
	flat_store_dwordx4 v[240:241], v[244:247] offset:64
	ds_read_b32 v131, v134 offset:256
	v_or_b32_e32 v132, 64, v130
	v_ashrrev_i32_e32 v133, 31, v132
	v_lshlrev_b64 v[132:133], 10, v[132:133]
	v_lshl_add_u64 v[132:133], v[128:129], 0, v[132:133]
	s_waitcnt lgkmcnt(0)
	v_mul_f32_e32 v135, v60, v131
	v_mul_f32_e32 v136, 0x3d372713, v135
	v_mul_f32_e32 v136, v135, v136
	v_fma_f32 v136, v135, v136, v135
	v_mul_f32_e32 v136, 0x3f4c422a, v136
	v_add_f32_e32 v136, v136, v136
	v_mul_f32_e32 v136, 0xbfb8aa3b, v136
	v_exp_f32_e32 v136, v136
	s_nop 0
	v_add_f32_e32 v136, 1.0, v136
	v_rcp_f32_e32 v136, v136
	s_nop 0
	v_mul_f32_e32 v135, v135, v136
	v_mul_f32_e32 v136, v56, v131
	v_mul_f32_e32 v137, 0x3d372713, v136
	v_mul_f32_e32 v137, v136, v137
	v_fma_f32 v137, v136, v137, v136
	v_mul_f32_e32 v137, 0x3f4c422a, v137
	v_add_f32_e32 v137, v137, v137
	v_mul_f32_e32 v137, 0xbfb8aa3b, v137
	v_exp_f32_e32 v137, v137
	s_nop 0
	v_add_f32_e32 v137, 1.0, v137
	v_rcp_f32_e32 v137, v137
	s_nop 0
	v_mul_f32_e32 v138, v136, v137
	v_mul_f32_e32 v136, v52, v131
	v_mul_f32_e32 v137, 0x3d372713, v136
	v_mul_f32_e32 v137, v136, v137
	v_fma_f32 v137, v136, v137, v136
	v_mul_f32_e32 v137, 0x3f4c422a, v137
	v_add_f32_e32 v137, v137, v137
	v_mul_f32_e32 v137, 0xbfb8aa3b, v137
	v_exp_f32_e32 v137, v137
	s_nop 0
	v_add_f32_e32 v137, 1.0, v137
	v_rcp_f32_e32 v137, v137
	s_nop 0
	v_mul_f32_e32 v139, v136, v137
	v_mul_f32_e32 v136, v48, v131
	v_mul_f32_e32 v137, 0x3d372713, v136
	v_mul_f32_e32 v137, v136, v137
	v_fma_f32 v137, v136, v137, v136
	v_mul_f32_e32 v137, 0x3f4c422a, v137
	v_add_f32_e32 v137, v137, v137
	v_mul_f32_e32 v137, 0xbfb8aa3b, v137
	v_exp_f32_e32 v137, v137
	s_nop 0
	v_add_f32_e32 v137, 1.0, v137
	v_rcp_f32_e32 v137, v137
	s_nop 0
	v_mul_f32_e32 v140, v136, v137
	v_mul_f32_e32 v136, v61, v131
	v_mul_f32_e32 v137, 0x3d372713, v136
	v_mul_f32_e32 v137, v136, v137
	v_fma_f32 v137, v136, v137, v136
	v_mul_f32_e32 v137, 0x3f4c422a, v137
	v_add_f32_e32 v137, v137, v137
	v_mul_f32_e32 v137, 0xbfb8aa3b, v137
	v_exp_f32_e32 v137, v137
	s_nop 0
	v_add_f32_e32 v137, 1.0, v137
	v_rcp_f32_e32 v137, v137
	s_nop 0
	v_mul_f32_e32 v136, v136, v137
	v_mul_f32_e32 v137, v57, v131
	v_mul_f32_e32 v141, 0x3d372713, v137
	v_mul_f32_e32 v141, v137, v141
	v_fma_f32 v141, v137, v141, v137
	v_mul_f32_e32 v141, 0x3f4c422a, v141
	v_add_f32_e32 v141, v141, v141
	v_mul_f32_e32 v141, 0xbfb8aa3b, v141
	v_exp_f32_e32 v141, v141
	v_cvt_pk_bf16_f32 v136, v135, v136
	s_nop 0
	v_add_f32_e32 v141, 1.0, v141
	v_rcp_f32_e32 v141, v141
	s_nop 0
	v_mul_f32_e32 v141, v137, v141
	v_mul_f32_e32 v137, v53, v131
	v_mul_f32_e32 v142, 0x3d372713, v137
	v_mul_f32_e32 v142, v137, v142
	v_fma_f32 v142, v137, v142, v137
	v_mul_f32_e32 v142, 0x3f4c422a, v142
	v_add_f32_e32 v142, v142, v142
	v_mul_f32_e32 v142, 0xbfb8aa3b, v142
	v_exp_f32_e32 v142, v142
	s_nop 0
	v_add_f32_e32 v142, 1.0, v142
	v_rcp_f32_e32 v142, v142
	s_nop 0
	v_mul_f32_e32 v142, v137, v142
	v_mul_f32_e32 v137, v49, v131
	v_mul_f32_e32 v143, 0x3d372713, v137
	v_mul_f32_e32 v143, v137, v143
	v_fma_f32 v143, v137, v143, v137
	v_mul_f32_e32 v143, 0x3f4c422a, v143
	v_add_f32_e32 v143, v143, v143
	v_mul_f32_e32 v143, 0xbfb8aa3b, v143
	v_exp_f32_e32 v143, v143
	s_nop 0
	v_add_f32_e32 v143, 1.0, v143
	v_rcp_f32_e32 v143, v143
	s_nop 0
	v_mul_f32_e32 v143, v137, v143
	v_mul_f32_e32 v137, v62, v131
	v_mul_f32_e32 v144, 0x3d372713, v137
	v_mul_f32_e32 v144, v137, v144
	v_fma_f32 v144, v137, v144, v137
	v_mul_f32_e32 v144, 0x3f4c422a, v144
	v_add_f32_e32 v144, v144, v144
	v_mul_f32_e32 v144, 0xbfb8aa3b, v144
	v_exp_f32_e32 v144, v144
	s_nop 0
	v_add_f32_e32 v144, 1.0, v144
	v_rcp_f32_e32 v144, v144
	s_nop 0
	v_mul_f32_e32 v137, v137, v144
	v_mul_f32_e32 v144, v58, v131
	v_mul_f32_e32 v146, 0x3d372713, v144
	v_mul_f32_e32 v146, v144, v146
	v_fma_f32 v146, v144, v146, v144
	v_mul_f32_e32 v146, 0x3f4c422a, v146
	v_add_f32_e32 v146, v146, v146
	v_mul_f32_e32 v146, 0xbfb8aa3b, v146
	v_exp_f32_e32 v146, v146
	s_nop 0
	v_add_f32_e32 v146, 1.0, v146
	v_rcp_f32_e32 v146, v146
	s_nop 0
	v_mul_f32_e32 v144, v144, v146
	v_mul_f32_e32 v146, v54, v131
	v_mul_f32_e32 v147, 0x3d372713, v146
	v_mul_f32_e32 v147, v146, v147
	v_fma_f32 v147, v146, v147, v146
	v_mul_f32_e32 v147, 0x3f4c422a, v147
	v_add_f32_e32 v147, v147, v147
	v_mul_f32_e32 v147, 0xbfb8aa3b, v147
	v_exp_f32_e32 v147, v147
	s_nop 0
	v_add_f32_e32 v147, 1.0, v147
	v_rcp_f32_e32 v147, v147
	s_nop 0
	v_mul_f32_e32 v146, v146, v147
	v_mul_f32_e32 v147, v50, v131
	v_mul_f32_e32 v148, 0x3d372713, v147
	v_mul_f32_e32 v148, v147, v148
	v_fma_f32 v148, v147, v148, v147
	v_mul_f32_e32 v148, 0x3f4c422a, v148
	v_add_f32_e32 v148, v148, v148
	v_mul_f32_e32 v148, 0xbfb8aa3b, v148
	v_exp_f32_e32 v148, v148
	s_nop 0
	v_add_f32_e32 v148, 1.0, v148
	v_rcp_f32_e32 v148, v148
	s_nop 0
	v_mul_f32_e32 v147, v147, v148
	v_mul_f32_e32 v148, v63, v131
	v_mul_f32_e32 v149, 0x3d372713, v148
	v_mul_f32_e32 v149, v148, v149
	v_fma_f32 v149, v148, v149, v148
	v_mul_f32_e32 v149, 0x3f4c422a, v149
	v_add_f32_e32 v149, v149, v149
	v_mul_f32_e32 v149, 0xbfb8aa3b, v149
	v_exp_f32_e32 v149, v149
	s_nop 0
	v_add_f32_e32 v149, 1.0, v149
	v_rcp_f32_e32 v149, v149
	s_nop 0
	v_mul_f32_e32 v148, v148, v149
	v_mul_f32_e32 v149, v59, v131
	v_mul_f32_e32 v155, 0x3d372713, v149
	v_mul_f32_e32 v155, v149, v155
	v_fma_f32 v155, v149, v155, v149
	v_mul_f32_e32 v155, 0x3f4c422a, v155
	v_add_f32_e32 v155, v155, v155
	v_mul_f32_e32 v155, 0xbfb8aa3b, v155
	v_exp_f32_e32 v155, v155
	v_cvt_pk_bf16_f32 v137, v137, v148
	v_mov_b32_e32 v248, v136
	v_mov_b32_e32 v249, v137
	v_cvt_pk_bf16_f32 v136, v138, v141
	v_add_f32_e32 v155, 1.0, v155
	v_rcp_f32_e32 v155, v155
	s_nop 0
	v_mul_f32_e32 v149, v149, v155
	v_mul_f32_e32 v155, v55, v131
	v_mul_f32_e32 v156, 0x3d372713, v155
	v_mul_f32_e32 v156, v155, v156
	v_fma_f32 v156, v155, v156, v155
	v_mul_f32_e32 v156, 0x3f4c422a, v156
	v_add_f32_e32 v156, v156, v156
	v_mul_f32_e32 v156, 0xbfb8aa3b, v156
	v_exp_f32_e32 v156, v156
	v_mul_f32_e32 v131, v51, v131
	v_cvt_pk_bf16_f32 v137, v144, v149
	v_mov_b32_e32 v250, v136
	v_mov_b32_e32 v251, v137
	v_add_f32_e32 v156, 1.0, v156
	v_rcp_f32_e32 v156, v156
	v_cvt_pk_bf16_f32 v136, v139, v142
	s_nop 0
	v_mul_f32_e32 v155, v155, v156
	v_mul_f32_e32 v156, 0x3d372713, v131
	v_mul_f32_e32 v156, v131, v156
	v_fma_f32 v156, v131, v156, v131
	v_mul_f32_e32 v156, 0x3f4c422a, v156
	v_add_f32_e32 v156, v156, v156
	v_mul_f32_e32 v156, 0xbfb8aa3b, v156
	v_exp_f32_e32 v156, v156
	v_cvt_pk_bf16_f32 v137, v146, v155
	v_mov_b32_e32 v244, v136
	v_mov_b32_e32 v245, v137
	v_cvt_pk_bf16_f32 v136, v140, v143
	v_add_f32_e32 v156, 1.0, v156
	v_rcp_f32_e32 v156, v156
	s_nop 0
	v_mul_f32_e32 v131, v131, v156
	v_cvt_pk_bf16_f32 v137, v147, v131
	v_mov_b32_e32 v246, v136
	v_mov_b32_e32 v247, v137
	v_and_b32_e32 v242, 16, v190
	v_mul_u32_u24_e32 v242, 3, v242
	v_lshrrev_b32_e32 v242, 1, v242
	v_mov_b32_e32 v243, 0
	v_lshl_add_u64 v[240:241], v[132:133], 0, v[242:243]
	v_permlane16_swap_b32 v248, v250
	v_permlane16_swap_b32 v249, v251
	v_permlane16_swap_b32 v244, v246
	v_permlane16_swap_b32 v245, v247
	flat_store_dwordx4 v[240:241], v[248:251]
	flat_store_dwordx4 v[240:241], v[244:247] offset:64
	ds_read_b32 v131, v134 offset:320
	v_or_b32_e32 v132, 0x50, v130
	v_ashrrev_i32_e32 v133, 31, v132
	v_lshlrev_b64 v[132:133], 10, v[132:133]
	v_lshl_add_u64 v[132:133], v[128:129], 0, v[132:133]
	s_waitcnt lgkmcnt(0)
	v_mul_f32_e32 v135, v44, v131
	v_mul_f32_e32 v136, 0x3d372713, v135
	v_mul_f32_e32 v136, v135, v136
	v_fma_f32 v136, v135, v136, v135
	v_mul_f32_e32 v136, 0x3f4c422a, v136
	v_add_f32_e32 v136, v136, v136
	v_mul_f32_e32 v136, 0xbfb8aa3b, v136
	v_exp_f32_e32 v136, v136
	s_nop 0
	v_add_f32_e32 v136, 1.0, v136
	v_rcp_f32_e32 v136, v136
	s_nop 0
	v_mul_f32_e32 v135, v135, v136
	v_mul_f32_e32 v136, v40, v131
	v_mul_f32_e32 v137, 0x3d372713, v136
	v_mul_f32_e32 v137, v136, v137
	v_fma_f32 v137, v136, v137, v136
	v_mul_f32_e32 v137, 0x3f4c422a, v137
	v_add_f32_e32 v137, v137, v137
	v_mul_f32_e32 v137, 0xbfb8aa3b, v137
	v_exp_f32_e32 v137, v137
	s_nop 0
	v_add_f32_e32 v137, 1.0, v137
	v_rcp_f32_e32 v137, v137
	s_nop 0
	v_mul_f32_e32 v138, v136, v137
	v_mul_f32_e32 v136, v36, v131
	v_mul_f32_e32 v137, 0x3d372713, v136
	v_mul_f32_e32 v137, v136, v137
	v_fma_f32 v137, v136, v137, v136
	v_mul_f32_e32 v137, 0x3f4c422a, v137
	v_add_f32_e32 v137, v137, v137
	v_mul_f32_e32 v137, 0xbfb8aa3b, v137
	v_exp_f32_e32 v137, v137
	s_nop 0
	v_add_f32_e32 v137, 1.0, v137
	v_rcp_f32_e32 v137, v137
	s_nop 0
	v_mul_f32_e32 v139, v136, v137
	v_mul_f32_e32 v136, v32, v131
	v_mul_f32_e32 v137, 0x3d372713, v136
	v_mul_f32_e32 v137, v136, v137
	v_fma_f32 v137, v136, v137, v136
	v_mul_f32_e32 v137, 0x3f4c422a, v137
	v_add_f32_e32 v137, v137, v137
	v_mul_f32_e32 v137, 0xbfb8aa3b, v137
	v_exp_f32_e32 v137, v137
	s_nop 0
	v_add_f32_e32 v137, 1.0, v137
	v_rcp_f32_e32 v137, v137
	s_nop 0
	v_mul_f32_e32 v140, v136, v137
	v_mul_f32_e32 v136, v45, v131
	v_mul_f32_e32 v137, 0x3d372713, v136
	v_mul_f32_e32 v137, v136, v137
	v_fma_f32 v137, v136, v137, v136
	v_mul_f32_e32 v137, 0x3f4c422a, v137
	v_add_f32_e32 v137, v137, v137
	v_mul_f32_e32 v137, 0xbfb8aa3b, v137
	v_exp_f32_e32 v137, v137
	s_nop 0
	v_add_f32_e32 v137, 1.0, v137
	v_rcp_f32_e32 v137, v137
	s_nop 0
	v_mul_f32_e32 v136, v136, v137
	v_mul_f32_e32 v137, v41, v131
	v_mul_f32_e32 v141, 0x3d372713, v137
	v_mul_f32_e32 v141, v137, v141
	v_fma_f32 v141, v137, v141, v137
	v_mul_f32_e32 v141, 0x3f4c422a, v141
	v_add_f32_e32 v141, v141, v141
	v_mul_f32_e32 v141, 0xbfb8aa3b, v141
	v_exp_f32_e32 v141, v141
	v_cvt_pk_bf16_f32 v136, v135, v136
	s_nop 0
	v_add_f32_e32 v141, 1.0, v141
	v_rcp_f32_e32 v141, v141
	s_nop 0
	v_mul_f32_e32 v141, v137, v141
	v_mul_f32_e32 v137, v37, v131
	v_mul_f32_e32 v142, 0x3d372713, v137
	v_mul_f32_e32 v142, v137, v142
	v_fma_f32 v142, v137, v142, v137
	v_mul_f32_e32 v142, 0x3f4c422a, v142
	v_add_f32_e32 v142, v142, v142
	v_mul_f32_e32 v142, 0xbfb8aa3b, v142
	v_exp_f32_e32 v142, v142
	s_nop 0
	v_add_f32_e32 v142, 1.0, v142
	v_rcp_f32_e32 v142, v142
	s_nop 0
	v_mul_f32_e32 v142, v137, v142
	v_mul_f32_e32 v137, v33, v131
	v_mul_f32_e32 v143, 0x3d372713, v137
	v_mul_f32_e32 v143, v137, v143
	v_fma_f32 v143, v137, v143, v137
	v_mul_f32_e32 v143, 0x3f4c422a, v143
	v_add_f32_e32 v143, v143, v143
	v_mul_f32_e32 v143, 0xbfb8aa3b, v143
	v_exp_f32_e32 v143, v143
	s_nop 0
	v_add_f32_e32 v143, 1.0, v143
	v_rcp_f32_e32 v143, v143
	s_nop 0
	v_mul_f32_e32 v143, v137, v143
	v_mul_f32_e32 v137, v46, v131
	v_mul_f32_e32 v144, 0x3d372713, v137
	v_mul_f32_e32 v144, v137, v144
	v_fma_f32 v144, v137, v144, v137
	v_mul_f32_e32 v144, 0x3f4c422a, v144
	v_add_f32_e32 v144, v144, v144
	v_mul_f32_e32 v144, 0xbfb8aa3b, v144
	v_exp_f32_e32 v144, v144
	s_nop 0
	v_add_f32_e32 v144, 1.0, v144
	v_rcp_f32_e32 v144, v144
	s_nop 0
	v_mul_f32_e32 v137, v137, v144
	v_mul_f32_e32 v144, v42, v131
	v_mul_f32_e32 v146, 0x3d372713, v144
	v_mul_f32_e32 v146, v144, v146
	v_fma_f32 v146, v144, v146, v144
	v_mul_f32_e32 v146, 0x3f4c422a, v146
	v_add_f32_e32 v146, v146, v146
	v_mul_f32_e32 v146, 0xbfb8aa3b, v146
	v_exp_f32_e32 v146, v146
	s_nop 0
	v_add_f32_e32 v146, 1.0, v146
	v_rcp_f32_e32 v146, v146
	s_nop 0
	v_mul_f32_e32 v144, v144, v146
	v_mul_f32_e32 v146, v38, v131
	v_mul_f32_e32 v147, 0x3d372713, v146
	v_mul_f32_e32 v147, v146, v147
	v_fma_f32 v147, v146, v147, v146
	v_mul_f32_e32 v147, 0x3f4c422a, v147
	v_add_f32_e32 v147, v147, v147
	v_mul_f32_e32 v147, 0xbfb8aa3b, v147
	v_exp_f32_e32 v147, v147
	s_nop 0
	v_add_f32_e32 v147, 1.0, v147
	v_rcp_f32_e32 v147, v147
	s_nop 0
	v_mul_f32_e32 v146, v146, v147
	v_mul_f32_e32 v147, v34, v131
	v_mul_f32_e32 v148, 0x3d372713, v147
	v_mul_f32_e32 v148, v147, v148
	v_fma_f32 v148, v147, v148, v147
	v_mul_f32_e32 v148, 0x3f4c422a, v148
	v_add_f32_e32 v148, v148, v148
	v_mul_f32_e32 v148, 0xbfb8aa3b, v148
	v_exp_f32_e32 v148, v148
	s_nop 0
	v_add_f32_e32 v148, 1.0, v148
	v_rcp_f32_e32 v148, v148
	s_nop 0
	v_mul_f32_e32 v147, v147, v148
	v_mul_f32_e32 v148, v47, v131
	v_mul_f32_e32 v149, 0x3d372713, v148
	v_mul_f32_e32 v149, v148, v149
	v_fma_f32 v149, v148, v149, v148
	v_mul_f32_e32 v149, 0x3f4c422a, v149
	v_add_f32_e32 v149, v149, v149
	v_mul_f32_e32 v149, 0xbfb8aa3b, v149
	v_exp_f32_e32 v149, v149
	s_nop 0
	v_add_f32_e32 v149, 1.0, v149
	v_rcp_f32_e32 v149, v149
	s_nop 0
	v_mul_f32_e32 v148, v148, v149
	v_mul_f32_e32 v149, v43, v131
	v_mul_f32_e32 v155, 0x3d372713, v149
	v_mul_f32_e32 v155, v149, v155
	v_fma_f32 v155, v149, v155, v149
	v_mul_f32_e32 v155, 0x3f4c422a, v155
	v_add_f32_e32 v155, v155, v155
	v_mul_f32_e32 v155, 0xbfb8aa3b, v155
	v_exp_f32_e32 v155, v155
	v_cvt_pk_bf16_f32 v137, v137, v148
	v_mov_b32_e32 v248, v136
	v_mov_b32_e32 v249, v137
	v_cvt_pk_bf16_f32 v136, v138, v141
	v_add_f32_e32 v155, 1.0, v155
	v_rcp_f32_e32 v155, v155
	s_nop 0
	v_mul_f32_e32 v149, v149, v155
	v_mul_f32_e32 v155, v39, v131
	v_mul_f32_e32 v156, 0x3d372713, v155
	v_mul_f32_e32 v156, v155, v156
	v_fma_f32 v156, v155, v156, v155
	v_mul_f32_e32 v156, 0x3f4c422a, v156
	v_add_f32_e32 v156, v156, v156
	v_mul_f32_e32 v156, 0xbfb8aa3b, v156
	v_exp_f32_e32 v156, v156
	v_mul_f32_e32 v131, v35, v131
	v_cvt_pk_bf16_f32 v137, v144, v149
	v_mov_b32_e32 v250, v136
	v_mov_b32_e32 v251, v137
	v_add_f32_e32 v156, 1.0, v156
	v_rcp_f32_e32 v156, v156
	v_cvt_pk_bf16_f32 v136, v139, v142
	s_nop 0
	v_mul_f32_e32 v155, v155, v156
	v_mul_f32_e32 v156, 0x3d372713, v131
	v_mul_f32_e32 v156, v131, v156
	v_fma_f32 v156, v131, v156, v131
	v_mul_f32_e32 v156, 0x3f4c422a, v156
	v_add_f32_e32 v156, v156, v156
	v_mul_f32_e32 v156, 0xbfb8aa3b, v156
	v_exp_f32_e32 v156, v156
	v_cvt_pk_bf16_f32 v137, v146, v155
	v_mov_b32_e32 v244, v136
	v_mov_b32_e32 v245, v137
	v_cvt_pk_bf16_f32 v136, v140, v143
	v_add_f32_e32 v156, 1.0, v156
	v_rcp_f32_e32 v156, v156
	s_nop 0
	v_mul_f32_e32 v131, v131, v156
	v_cvt_pk_bf16_f32 v137, v147, v131
	v_mov_b32_e32 v246, v136
	v_mov_b32_e32 v247, v137
	v_and_b32_e32 v242, 16, v190
	v_mul_u32_u24_e32 v242, 3, v242
	v_lshrrev_b32_e32 v242, 1, v242
	v_mov_b32_e32 v243, 0
	v_lshl_add_u64 v[240:241], v[132:133], 0, v[242:243]
	v_permlane16_swap_b32 v248, v250
	v_permlane16_swap_b32 v249, v251
	v_permlane16_swap_b32 v244, v246
	v_permlane16_swap_b32 v245, v247
	flat_store_dwordx4 v[240:241], v[248:251]
	flat_store_dwordx4 v[240:241], v[244:247] offset:64
	ds_read_b32 v131, v134 offset:384
	v_or_b32_e32 v132, 0x60, v130
	v_ashrrev_i32_e32 v133, 31, v132
	v_lshlrev_b64 v[132:133], 10, v[132:133]
	v_lshl_add_u64 v[132:133], v[128:129], 0, v[132:133]
	s_waitcnt lgkmcnt(0)
	v_mul_f32_e32 v135, v28, v131
	v_mul_f32_e32 v136, 0x3d372713, v135
	v_mul_f32_e32 v136, v135, v136
	v_fma_f32 v136, v135, v136, v135
	v_mul_f32_e32 v136, 0x3f4c422a, v136
	v_add_f32_e32 v136, v136, v136
	v_mul_f32_e32 v136, 0xbfb8aa3b, v136
	v_exp_f32_e32 v136, v136
	v_or_b32_e32 v130, 0x70, v130
	v_add_f32_e32 v136, 1.0, v136
	v_rcp_f32_e32 v136, v136
	s_nop 0
	v_mul_f32_e32 v135, v135, v136
	v_mul_f32_e32 v136, v24, v131
	v_mul_f32_e32 v137, 0x3d372713, v136
	v_mul_f32_e32 v137, v136, v137
	v_fma_f32 v137, v136, v137, v136
	v_mul_f32_e32 v137, 0x3f4c422a, v137
	v_add_f32_e32 v137, v137, v137
	v_mul_f32_e32 v137, 0xbfb8aa3b, v137
	v_exp_f32_e32 v137, v137
	s_nop 0
	v_add_f32_e32 v137, 1.0, v137
	v_rcp_f32_e32 v137, v137
	s_nop 0
	v_mul_f32_e32 v138, v136, v137
	v_mul_f32_e32 v136, v20, v131
	v_mul_f32_e32 v137, 0x3d372713, v136
	v_mul_f32_e32 v137, v136, v137
	v_fma_f32 v137, v136, v137, v136
	v_mul_f32_e32 v137, 0x3f4c422a, v137
	v_add_f32_e32 v137, v137, v137
	v_mul_f32_e32 v137, 0xbfb8aa3b, v137
	v_exp_f32_e32 v137, v137
	s_nop 0
	v_add_f32_e32 v137, 1.0, v137
	v_rcp_f32_e32 v137, v137
	s_nop 0
	v_mul_f32_e32 v139, v136, v137
	v_mul_f32_e32 v136, v16, v131
	v_mul_f32_e32 v137, 0x3d372713, v136
	v_mul_f32_e32 v137, v136, v137
	v_fma_f32 v137, v136, v137, v136
	v_mul_f32_e32 v137, 0x3f4c422a, v137
	v_add_f32_e32 v137, v137, v137
	v_mul_f32_e32 v137, 0xbfb8aa3b, v137
	v_exp_f32_e32 v137, v137
	s_nop 0
	v_add_f32_e32 v137, 1.0, v137
	v_rcp_f32_e32 v137, v137
	s_nop 0
	v_mul_f32_e32 v140, v136, v137
	v_mul_f32_e32 v136, v29, v131
	v_mul_f32_e32 v137, 0x3d372713, v136
	v_mul_f32_e32 v137, v136, v137
	v_fma_f32 v137, v136, v137, v136
	v_mul_f32_e32 v137, 0x3f4c422a, v137
	v_add_f32_e32 v137, v137, v137
	v_mul_f32_e32 v137, 0xbfb8aa3b, v137
	v_exp_f32_e32 v137, v137
	s_nop 0
	v_add_f32_e32 v137, 1.0, v137
	v_rcp_f32_e32 v137, v137
	s_nop 0
	v_mul_f32_e32 v136, v136, v137
	v_mul_f32_e32 v137, v25, v131
	v_mul_f32_e32 v141, 0x3d372713, v137
	v_mul_f32_e32 v141, v137, v141
	v_fma_f32 v141, v137, v141, v137
	v_mul_f32_e32 v141, 0x3f4c422a, v141
	v_add_f32_e32 v141, v141, v141
	v_mul_f32_e32 v141, 0xbfb8aa3b, v141
	v_exp_f32_e32 v141, v141
	v_cvt_pk_bf16_f32 v136, v135, v136
	s_nop 0
	v_add_f32_e32 v141, 1.0, v141
	v_rcp_f32_e32 v141, v141
	s_nop 0
	v_mul_f32_e32 v141, v137, v141
	v_mul_f32_e32 v137, v21, v131
	v_mul_f32_e32 v142, 0x3d372713, v137
	v_mul_f32_e32 v142, v137, v142
	v_fma_f32 v142, v137, v142, v137
	v_mul_f32_e32 v142, 0x3f4c422a, v142
	v_add_f32_e32 v142, v142, v142
	v_mul_f32_e32 v142, 0xbfb8aa3b, v142
	v_exp_f32_e32 v142, v142
	s_nop 0
	v_add_f32_e32 v142, 1.0, v142
	v_rcp_f32_e32 v142, v142
	s_nop 0
	v_mul_f32_e32 v142, v137, v142
	v_mul_f32_e32 v137, v17, v131
	v_mul_f32_e32 v143, 0x3d372713, v137
	v_mul_f32_e32 v143, v137, v143
	v_fma_f32 v143, v137, v143, v137
	v_mul_f32_e32 v143, 0x3f4c422a, v143
	v_add_f32_e32 v143, v143, v143
	v_mul_f32_e32 v143, 0xbfb8aa3b, v143
	v_exp_f32_e32 v143, v143
	s_nop 0
	v_add_f32_e32 v143, 1.0, v143
	v_rcp_f32_e32 v143, v143
	s_nop 0
	v_mul_f32_e32 v143, v137, v143
	v_mul_f32_e32 v137, v30, v131
	v_mul_f32_e32 v144, 0x3d372713, v137
	v_mul_f32_e32 v144, v137, v144
	v_fma_f32 v144, v137, v144, v137
	v_mul_f32_e32 v144, 0x3f4c422a, v144
	v_add_f32_e32 v144, v144, v144
	v_mul_f32_e32 v144, 0xbfb8aa3b, v144
	v_exp_f32_e32 v144, v144
	s_nop 0
	v_add_f32_e32 v144, 1.0, v144
	v_rcp_f32_e32 v144, v144
	s_nop 0
	v_mul_f32_e32 v137, v137, v144
	v_mul_f32_e32 v144, v26, v131
	v_mul_f32_e32 v146, 0x3d372713, v144
	v_mul_f32_e32 v146, v144, v146
	v_fma_f32 v146, v144, v146, v144
	v_mul_f32_e32 v146, 0x3f4c422a, v146
	v_add_f32_e32 v146, v146, v146
	v_mul_f32_e32 v146, 0xbfb8aa3b, v146
	v_exp_f32_e32 v146, v146
	s_nop 0
	v_add_f32_e32 v146, 1.0, v146
	v_rcp_f32_e32 v146, v146
	s_nop 0
	v_mul_f32_e32 v144, v144, v146
	v_mul_f32_e32 v146, v22, v131
	v_mul_f32_e32 v147, 0x3d372713, v146
	v_mul_f32_e32 v147, v146, v147
	v_fma_f32 v147, v146, v147, v146
	v_mul_f32_e32 v147, 0x3f4c422a, v147
	v_add_f32_e32 v147, v147, v147
	v_mul_f32_e32 v147, 0xbfb8aa3b, v147
	v_exp_f32_e32 v147, v147
	s_nop 0
	v_add_f32_e32 v147, 1.0, v147
	v_rcp_f32_e32 v147, v147
	s_nop 0
	v_mul_f32_e32 v146, v146, v147
	v_mul_f32_e32 v147, v18, v131
	v_mul_f32_e32 v148, 0x3d372713, v147
	v_mul_f32_e32 v148, v147, v148
	v_fma_f32 v148, v147, v148, v147
	v_mul_f32_e32 v148, 0x3f4c422a, v148
	v_add_f32_e32 v148, v148, v148
	v_mul_f32_e32 v148, 0xbfb8aa3b, v148
	v_exp_f32_e32 v148, v148
	s_nop 0
	v_add_f32_e32 v148, 1.0, v148
	v_rcp_f32_e32 v148, v148
	s_nop 0
	v_mul_f32_e32 v147, v147, v148
	v_mul_f32_e32 v148, v31, v131
	v_mul_f32_e32 v149, 0x3d372713, v148
	v_mul_f32_e32 v149, v148, v149
	v_fma_f32 v149, v148, v149, v148
	v_mul_f32_e32 v149, 0x3f4c422a, v149
	v_add_f32_e32 v149, v149, v149
	v_mul_f32_e32 v149, 0xbfb8aa3b, v149
	v_exp_f32_e32 v149, v149
	s_nop 0
	v_add_f32_e32 v149, 1.0, v149
	v_rcp_f32_e32 v149, v149
	s_nop 0
	v_mul_f32_e32 v148, v148, v149
	v_mul_f32_e32 v149, v27, v131
	v_mul_f32_e32 v155, 0x3d372713, v149
	v_mul_f32_e32 v155, v149, v155
	v_fma_f32 v155, v149, v155, v149
	v_mul_f32_e32 v155, 0x3f4c422a, v155
	v_add_f32_e32 v155, v155, v155
	v_mul_f32_e32 v155, 0xbfb8aa3b, v155
	v_exp_f32_e32 v155, v155
	v_cvt_pk_bf16_f32 v137, v137, v148
	v_mov_b32_e32 v248, v136
	v_mov_b32_e32 v249, v137
	v_cvt_pk_bf16_f32 v136, v138, v141
	v_add_f32_e32 v155, 1.0, v155
	v_rcp_f32_e32 v155, v155
	s_nop 0
	v_mul_f32_e32 v149, v149, v155
	v_mul_f32_e32 v155, v23, v131
	v_mul_f32_e32 v156, 0x3d372713, v155
	v_mul_f32_e32 v156, v155, v156
	v_fma_f32 v156, v155, v156, v155
	v_mul_f32_e32 v156, 0x3f4c422a, v156
	v_add_f32_e32 v156, v156, v156
	v_mul_f32_e32 v156, 0xbfb8aa3b, v156
	v_exp_f32_e32 v156, v156
	v_mul_f32_e32 v131, v19, v131
	v_cvt_pk_bf16_f32 v137, v144, v149
	v_mov_b32_e32 v250, v136
	v_mov_b32_e32 v251, v137
	v_add_f32_e32 v156, 1.0, v156
	v_rcp_f32_e32 v156, v156
	v_cvt_pk_bf16_f32 v136, v139, v142
	s_nop 0
	v_mul_f32_e32 v155, v155, v156
	v_mul_f32_e32 v156, 0x3d372713, v131
	v_mul_f32_e32 v156, v131, v156
	v_fma_f32 v156, v131, v156, v131
	v_mul_f32_e32 v156, 0x3f4c422a, v156
	v_add_f32_e32 v156, v156, v156
	v_mul_f32_e32 v156, 0xbfb8aa3b, v156
	v_exp_f32_e32 v156, v156
	v_cvt_pk_bf16_f32 v137, v146, v155
	v_mov_b32_e32 v244, v136
	v_mov_b32_e32 v245, v137
	v_cvt_pk_bf16_f32 v136, v140, v143
	v_add_f32_e32 v156, 1.0, v156
	v_rcp_f32_e32 v156, v156
	s_nop 0
	v_mul_f32_e32 v131, v131, v156
	v_cvt_pk_bf16_f32 v137, v147, v131
	v_mov_b32_e32 v246, v136
	v_mov_b32_e32 v247, v137
	v_and_b32_e32 v242, 16, v190
	v_mul_u32_u24_e32 v242, 3, v242
	v_lshrrev_b32_e32 v242, 1, v242
	v_mov_b32_e32 v243, 0
	v_lshl_add_u64 v[240:241], v[132:133], 0, v[242:243]
	v_permlane16_swap_b32 v248, v250
	v_permlane16_swap_b32 v249, v251
	v_permlane16_swap_b32 v244, v246
	v_permlane16_swap_b32 v245, v247
	flat_store_dwordx4 v[240:241], v[248:251]
	flat_store_dwordx4 v[240:241], v[244:247] offset:64
	ds_read_b32 v132, v134 offset:448
	v_ashrrev_i32_e32 v131, 31, v130
	v_lshlrev_b64 v[130:131], 10, v[130:131]
	v_lshl_add_u64 v[128:129], v[128:129], 0, v[130:131]
	s_waitcnt lgkmcnt(0)
	v_mul_f32_e32 v133, v0, v132
	v_mul_f32_e32 v134, 0x3d372713, v133
	v_mul_f32_e32 v134, v133, v134
	v_fma_f32 v134, v133, v134, v133
	v_mul_f32_e32 v134, 0x3f4c422a, v134
	v_add_f32_e32 v134, v134, v134
	v_mul_f32_e32 v134, 0xbfb8aa3b, v134
	v_exp_f32_e32 v134, v134
	s_nop 0
	v_add_f32_e32 v134, 1.0, v134
	v_rcp_f32_e32 v134, v134
	s_nop 0
	v_mul_f32_e32 v133, v133, v134
	v_mul_f32_e32 v134, v4, v132
	v_mul_f32_e32 v135, 0x3d372713, v134
	v_mul_f32_e32 v135, v134, v135
	v_fma_f32 v135, v134, v135, v134
	v_mul_f32_e32 v135, 0x3f4c422a, v135
	v_add_f32_e32 v135, v135, v135
	v_mul_f32_e32 v135, 0xbfb8aa3b, v135
	v_exp_f32_e32 v135, v135
	s_nop 0
	v_add_f32_e32 v135, 1.0, v135
	v_rcp_f32_e32 v135, v135
	s_nop 0
	v_mul_f32_e32 v134, v134, v135
	v_mul_f32_e32 v135, v8, v132
	v_mul_f32_e32 v136, 0x3d372713, v135
	v_mul_f32_e32 v136, v135, v136
	v_fma_f32 v136, v135, v136, v135
	v_mul_f32_e32 v136, 0x3f4c422a, v136
	v_add_f32_e32 v136, v136, v136
	v_mul_f32_e32 v136, 0xbfb8aa3b, v136
	v_exp_f32_e32 v136, v136
	s_nop 0
	v_add_f32_e32 v136, 1.0, v136
	v_rcp_f32_e32 v136, v136
	s_nop 0
	v_mul_f32_e32 v135, v135, v136
	v_mul_f32_e32 v136, v12, v132
	v_mul_f32_e32 v137, 0x3d372713, v136
	v_mul_f32_e32 v137, v136, v137
	v_fma_f32 v137, v136, v137, v136
	v_mul_f32_e32 v137, 0x3f4c422a, v137
	v_add_f32_e32 v137, v137, v137
	v_mul_f32_e32 v137, 0xbfb8aa3b, v137
	v_exp_f32_e32 v137, v137
	s_nop 0
	v_add_f32_e32 v137, 1.0, v137
	v_rcp_f32_e32 v137, v137
	s_nop 0
	v_mul_f32_e32 v136, v136, v137
	v_mul_f32_e32 v137, v1, v132
	v_mul_f32_e32 v138, 0x3d372713, v137
	v_mul_f32_e32 v138, v137, v138
	v_fma_f32 v138, v137, v138, v137
	v_mul_f32_e32 v138, 0x3f4c422a, v138
	v_add_f32_e32 v138, v138, v138
	v_mul_f32_e32 v138, 0xbfb8aa3b, v138
	v_exp_f32_e32 v138, v138
	s_nop 0
	v_add_f32_e32 v138, 1.0, v138
	v_rcp_f32_e32 v138, v138
	s_nop 0
	v_mul_f32_e32 v137, v137, v138
	v_mul_f32_e32 v138, v5, v132
	v_mul_f32_e32 v139, 0x3d372713, v138
	v_mul_f32_e32 v139, v138, v139
	v_fma_f32 v139, v138, v139, v138
	v_mul_f32_e32 v139, 0x3f4c422a, v139
	v_add_f32_e32 v139, v139, v139
	v_mul_f32_e32 v139, 0xbfb8aa3b, v139
	v_exp_f32_e32 v139, v139
	v_cvt_pk_bf16_f32 v130, v133, v137
	s_nop 0
	v_add_f32_e32 v139, 1.0, v139
	v_rcp_f32_e32 v139, v139
	s_nop 0
	v_mul_f32_e32 v138, v138, v139
	v_mul_f32_e32 v139, v9, v132
	v_mul_f32_e32 v140, 0x3d372713, v139
	v_mul_f32_e32 v140, v139, v140
	v_fma_f32 v140, v139, v140, v139
	v_mul_f32_e32 v140, 0x3f4c422a, v140
	v_add_f32_e32 v140, v140, v140
	v_mul_f32_e32 v140, 0xbfb8aa3b, v140
	v_exp_f32_e32 v140, v140
	s_nop 0
	v_add_f32_e32 v140, 1.0, v140
	v_rcp_f32_e32 v140, v140
	s_nop 0
	v_mul_f32_e32 v139, v139, v140
	v_mul_f32_e32 v140, v13, v132
	v_mul_f32_e32 v141, 0x3d372713, v140
	v_mul_f32_e32 v141, v140, v141
	v_fma_f32 v141, v140, v141, v140
	v_mul_f32_e32 v141, 0x3f4c422a, v141
	v_add_f32_e32 v141, v141, v141
	v_mul_f32_e32 v141, 0xbfb8aa3b, v141
	v_exp_f32_e32 v141, v141
	s_nop 0
	v_add_f32_e32 v141, 1.0, v141
	v_rcp_f32_e32 v141, v141
	s_nop 0
	v_mul_f32_e32 v140, v140, v141
	v_mul_f32_e32 v141, v2, v132
	v_mul_f32_e32 v142, 0x3d372713, v141
	v_mul_f32_e32 v142, v141, v142
	v_fma_f32 v142, v141, v142, v141
	v_mul_f32_e32 v142, 0x3f4c422a, v142
	v_add_f32_e32 v142, v142, v142
	v_mul_f32_e32 v142, 0xbfb8aa3b, v142
	v_exp_f32_e32 v142, v142
	s_nop 0
	v_add_f32_e32 v142, 1.0, v142
	v_rcp_f32_e32 v142, v142
	s_nop 0
	v_mul_f32_e32 v141, v141, v142
	v_mul_f32_e32 v142, v6, v132
	v_mul_f32_e32 v143, 0x3d372713, v142
	v_mul_f32_e32 v143, v142, v143
	v_fma_f32 v143, v142, v143, v142
	v_mul_f32_e32 v143, 0x3f4c422a, v143
	v_add_f32_e32 v143, v143, v143
	v_mul_f32_e32 v143, 0xbfb8aa3b, v143
	v_exp_f32_e32 v143, v143
	s_nop 0
	v_add_f32_e32 v143, 1.0, v143
	v_rcp_f32_e32 v143, v143
	s_nop 0
	v_mul_f32_e32 v142, v142, v143
	v_mul_f32_e32 v143, v10, v132
	v_mul_f32_e32 v144, 0x3d372713, v143
	v_mul_f32_e32 v144, v143, v144
	v_fma_f32 v144, v143, v144, v143
	v_mul_f32_e32 v144, 0x3f4c422a, v144
	v_add_f32_e32 v144, v144, v144
	v_mul_f32_e32 v144, 0xbfb8aa3b, v144
	v_exp_f32_e32 v144, v144
	s_nop 0
	v_add_f32_e32 v144, 1.0, v144
	v_rcp_f32_e32 v144, v144
	s_nop 0
	v_mul_f32_e32 v143, v143, v144
	v_mul_f32_e32 v144, v14, v132
	v_mul_f32_e32 v146, 0x3d372713, v144
	v_mul_f32_e32 v146, v144, v146
	v_fma_f32 v146, v144, v146, v144
	v_mul_f32_e32 v146, 0x3f4c422a, v146
	v_add_f32_e32 v146, v146, v146
	v_mul_f32_e32 v146, 0xbfb8aa3b, v146
	v_exp_f32_e32 v146, v146
	s_nop 0
	v_add_f32_e32 v146, 1.0, v146
	v_rcp_f32_e32 v146, v146
	s_nop 0
	v_mul_f32_e32 v144, v144, v146
	v_mul_f32_e32 v146, v3, v132
	v_mul_f32_e32 v147, 0x3d372713, v146
	v_mul_f32_e32 v147, v146, v147
	v_fma_f32 v147, v146, v147, v146
	v_mul_f32_e32 v147, 0x3f4c422a, v147
	v_add_f32_e32 v147, v147, v147
	v_mul_f32_e32 v147, 0xbfb8aa3b, v147
	v_exp_f32_e32 v147, v147
	s_nop 0
	v_add_f32_e32 v147, 1.0, v147
	v_rcp_f32_e32 v147, v147
	s_nop 0
	v_mul_f32_e32 v146, v146, v147
	v_mul_f32_e32 v147, v7, v132
	v_mul_f32_e32 v148, 0x3d372713, v147
	v_mul_f32_e32 v148, v147, v148
	v_fma_f32 v148, v147, v148, v147
	v_mul_f32_e32 v148, 0x3f4c422a, v148
	v_add_f32_e32 v148, v148, v148
	v_mul_f32_e32 v148, 0xbfb8aa3b, v148
	v_exp_f32_e32 v148, v148
	v_cvt_pk_bf16_f32 v131, v141, v146
	v_mov_b32_e32 v248, v130
	v_mov_b32_e32 v249, v131
	v_cvt_pk_bf16_f32 v130, v134, v138
	v_add_f32_e32 v148, 1.0, v148
	v_rcp_f32_e32 v148, v148
	s_nop 0
	v_mul_f32_e32 v147, v147, v148
	v_mul_f32_e32 v148, v11, v132
	v_mul_f32_e32 v149, 0x3d372713, v148
	v_mul_f32_e32 v149, v148, v149
	v_fma_f32 v149, v148, v149, v148
	v_mul_f32_e32 v149, 0x3f4c422a, v149
	v_add_f32_e32 v149, v149, v149
	v_mul_f32_e32 v149, 0xbfb8aa3b, v149
	v_exp_f32_e32 v149, v149
	v_mul_f32_e32 v132, v15, v132
	v_cvt_pk_bf16_f32 v131, v142, v147
	v_mov_b32_e32 v250, v130
	v_mov_b32_e32 v251, v131
	v_add_f32_e32 v149, 1.0, v149
	v_rcp_f32_e32 v149, v149
	v_cvt_pk_bf16_f32 v130, v135, v139
	s_nop 0
	v_mul_f32_e32 v148, v148, v149
	v_mul_f32_e32 v149, 0x3d372713, v132
	v_mul_f32_e32 v149, v132, v149
	v_fma_f32 v149, v132, v149, v132
	v_mul_f32_e32 v149, 0x3f4c422a, v149
	v_add_f32_e32 v149, v149, v149
	v_mul_f32_e32 v149, 0xbfb8aa3b, v149
	v_exp_f32_e32 v149, v149
	v_cvt_pk_bf16_f32 v131, v143, v148
	v_mov_b32_e32 v244, v130
	v_mov_b32_e32 v245, v131
	v_cvt_pk_bf16_f32 v130, v136, v140
	v_add_f32_e32 v149, 1.0, v149
	v_rcp_f32_e32 v149, v149
	s_nop 0
	v_mul_f32_e32 v132, v132, v149
	v_cvt_pk_bf16_f32 v131, v144, v132
	v_mov_b32_e32 v246, v130
	v_mov_b32_e32 v247, v131
	v_and_b32_e32 v242, 16, v190
	v_mul_u32_u24_e32 v242, 3, v242
	v_lshrrev_b32_e32 v242, 1, v242
	v_mov_b32_e32 v243, 0
	v_lshl_add_u64 v[240:241], v[128:129], 0, v[242:243]
	v_permlane16_swap_b32 v248, v250
	v_permlane16_swap_b32 v249, v251
	v_permlane16_swap_b32 v244, v246
	v_permlane16_swap_b32 v245, v247
	flat_store_dwordx4 v[240:241], v[248:251]
	flat_store_dwordx4 v[240:241], v[244:247] offset:64

.LBB0_461:
	s_or_b64 exec, exec, s[2:3]
	v_or_b32_e32 v146, s26, v159
	v_lshl_add_u32 v158, v160, 7, v146
	v_lshlrev_b32_e32 v146, 2, v159
	v_lshl_or_b32 v146, v160, 9, v146
	v_and_b32_e32 v147, 64, v194
	v_add_u32_e32 v218, 0x20800, v146
	v_xor_b32_e32 v146, 16, v194
	v_add_u32_e32 v147, 64, v147
	v_cmp_lt_i32_e64 s[6:7], v146, v147
	v_lshl_add_u64 v[128:129], s[8:9], 2, v[128:129]
	v_lshlrev_b32_e32 v144, 4, v151
	v_cndmask_b32_e64 v146, v194, v146, s[6:7]
	v_lshlrev_b32_e32 v216, 2, v146
	v_xor_b32_e32 v146, 32, v194
	v_cmp_lt_i32_e64 s[6:7], v146, v147
	v_lshl_add_u64 v[128:129], v[128:129], 0, v[144:145]
	flat_load_dwordx4 v[140:143], v[128:129]
	flat_load_dwordx4 v[136:139], v[128:129] offset:64
	s_waitcnt lgkmcnt(0)
	flat_load_dwordx4 v[132:135], v[128:129] offset:128
	s_nop 0
	flat_load_dwordx4 v[128:131], v[128:129] offset:192
	v_cndmask_b32_e64 v146, v194, v146, s[6:7]
	v_lshlrev_b32_e32 v217, 2, v146
	v_lshl_add_u64 v[146:147], s[20:21], 0, v[144:145]
	ds_read_b32 v144, v218
	s_mov_b64 s[2:3], 0x122e0000
	v_lshl_add_u64 v[160:161], v[146:147], 0, s[2:3]
	s_mov_b64 s[2:3], 0x122e1000
	v_lshl_add_u64 v[162:163], v[146:147], 0, s[2:3]
	s_waitcnt lgkmcnt(0)
	v_pk_mul_f32 v[186:187], v[124:125], v[144:145] op_sel_hi:[1,0]
	v_pk_mul_f32 v[178:179], v[116:117], v[144:145] op_sel_hi:[1,0]
	v_mul_f32_e32 v116, v187, v187
	v_pk_mul_f32 v[184:185], v[126:127], v[144:145] op_sel_hi:[1,0]
	v_fmac_f32_e32 v116, v186, v186
	v_fmac_f32_e32 v116, v184, v184
	v_pk_mul_f32 v[182:183], v[120:121], v[144:145] op_sel_hi:[1,0]
	v_fmac_f32_e32 v116, v185, v185
	v_fmac_f32_e32 v116, v182, v182
	v_pk_mul_f32 v[180:181], v[122:123], v[144:145] op_sel_hi:[1,0]
	v_fmac_f32_e32 v116, v183, v183
	v_fmac_f32_e32 v116, v180, v180
	v_pk_mul_f32 v[172:173], v[114:115], v[144:145] op_sel_hi:[1,0]
	v_fmac_f32_e32 v116, v181, v181
	v_pk_mul_f32 v[114:115], v[178:179], v[178:179]
	v_pk_mul_f32 v[176:177], v[118:119], v[144:145] op_sel_hi:[1,0]
	v_add_f32_e32 v114, v114, v116
	v_pk_mul_f32 v[174:175], v[112:113], v[144:145] op_sel_hi:[1,0]
	v_pk_mul_f32 v[112:113], v[176:177], v[176:177]
	v_add_f32_e32 v114, v115, v114
	v_add_f32_e32 v112, v112, v114
	v_add_f32_e32 v116, v113, v112
	v_pk_mul_f32 v[114:115], v[174:175], v[174:175]
	v_pk_mul_f32 v[112:113], v[172:173], v[172:173]
	v_add_f32_e32 v114, v114, v116
	v_add_f32_e32 v114, v115, v114
	v_add_f32_e32 v112, v112, v114
	v_add_f32_e32 v112, v113, v112
	ds_bpermute_b32 v113, v216, v112
	v_and_b32_e32 v144, 0xf80, v158
	v_lshl_add_u64 v[168:169], v[160:161], 0, v[144:145]
	v_lshl_add_u64 v[170:171], v[162:163], 0, v[144:145]
	v_lshlrev_b32_e32 v144, 6, v159
	v_lshl_add_u64 v[164:165], v[160:161], 0, v[144:145]
	v_lshl_add_u64 v[166:167], v[162:163], 0, v[144:145]
	s_waitcnt lgkmcnt(0)
	v_add_f32_e32 v219, v112, v113
	flat_load_dwordx4 v[116:119], v[168:169]
	flat_load_dwordx4 v[124:127], v[170:171]
	flat_load_dwordx4 v[112:115], v[164:165]
	flat_load_dwordx4 v[120:123], v[166:167]
	ds_bpermute_b32 v220, v217, v219
	v_mov_b32_e32 v155, v145
	v_lshl_add_u64 v[156:157], v[154:155], 1, s[20:21]
	v_ashrrev_i32_e32 v159, 31, v158
	s_and_saveexec_b64 s[2:3], vcc
	s_xor_b64 s[2:3], exec, s[2:3]
	v_lshlrev_b64 v[146:147], 8, v[158:159]
	v_lshl_add_u64 v[146:147], v[156:157], 0, v[146:147]
	s_mov_b64 s[6:7], 0x69dfc00
	v_lshl_add_u64 v[188:189], v[146:147], 0, s[6:7]
	s_or_saveexec_b64 s[2:3], s[2:3]
	v_ashrrev_i32_e32 v155, 31, v154
	v_lshl_add_u64 v[146:147], v[154:155], 1, s[20:21]
	s_mov_b64 s[6:7], 0x59e0000
	v_lshl_add_u64 v[154:155], v[146:147], 0, s[6:7]
	s_xor_b64 exec, exec, s[2:3]
	v_lshlrev_b64 v[146:147], 10, v[158:159]
	v_lshl_add_u64 v[188:189], v[154:155], 0, v[146:147]
	s_or_b64 exec, exec, s[2:3]
	s_waitcnt lgkmcnt(0)
	v_add_f32_e32 v144, v219, v220
	v_fmamk_f32 v144, v144, 0x3c800000, v192
	v_mul_f32_e32 v146, 0x4b800000, v144
	v_cmp_gt_f32_e64 s[6:7], s58, v144
	v_lshlrev_b32_e32 v151, 2, v151
	s_nop 0
	v_cndmask_b32_e64 v144, v144, v146, s[6:7]
	v_rsq_f32_e32 v144, v144
	s_nop 0
	v_mul_f32_e32 v146, 0x45800000, v144
	v_cndmask_b32_e64 v144, v144, v146, s[6:7]
	v_pk_mul_f32 v[148:149], v[186:187], v[144:145] op_sel_hi:[1,0]
	v_pk_mul_f32 v[182:183], v[182:183], v[144:145] op_sel_hi:[1,0]
	v_pk_mul_f32 v[146:147], v[184:185], v[144:145] op_sel_hi:[1,0]
	s_waitcnt vmcnt(0)
	v_pk_mul_f32 v[148:149], v[140:141], v[148:149]
	v_pk_mul_f32 v[180:181], v[180:181], v[144:145] op_sel_hi:[1,0]
	v_pk_mul_f32 v[182:183], v[136:137], v[182:183]
	v_pk_mul_f32 v[178:179], v[178:179], v[144:145] op_sel_hi:[1,0]
	v_pk_mul_f32 v[174:175], v[174:175], v[144:145] op_sel_hi:[1,0]
	v_pk_mul_f32 v[146:147], v[142:143], v[146:147]
	v_pk_mul_f32 v[180:181], v[138:139], v[180:181]
	v_pk_mul_f32 v[176:177], v[176:177], v[144:145] op_sel_hi:[1,0]
	v_pk_mul_f32 v[178:179], v[132:133], v[178:179]
	v_pk_mul_f32 v[172:173], v[172:173], v[144:145] op_sel_hi:[1,0]
	v_pk_mul_f32 v[174:175], v[128:129], v[174:175]
	v_pk_mul_f32 v[184:185], v[124:125], v[182:183]
	v_pk_mul_f32 v[124:125], v[124:125], v[148:149]
	v_pk_mul_f32 v[176:177], v[134:135], v[176:177]
	v_pk_mul_f32 v[172:173], v[130:131], v[172:173]
	v_pk_mul_f32 v[186:187], v[126:127], v[180:181]
	v_pk_fma_f32 v[184:185], v[116:117], v[148:149], v[184:185] neg_lo:[0,0,1] neg_hi:[0,0,1]
	v_pk_mul_f32 v[126:127], v[126:127], v[146:147]
	v_pk_fma_f32 v[116:117], v[116:117], v[182:183], v[124:125]
	v_pk_mul_f32 v[124:125], v[120:121], v[174:175]
	v_pk_mul_f32 v[120:121], v[120:121], v[178:179]
	v_pk_fma_f32 v[186:187], v[118:119], v[146:147], v[186:187] neg_lo:[0,0,1] neg_hi:[0,0,1]
	v_pk_fma_f32 v[118:119], v[118:119], v[180:181], v[126:127]
	v_pk_mul_f32 v[126:127], v[122:123], v[172:173]
	v_pk_fma_f32 v[124:125], v[112:113], v[178:179], v[124:125] neg_lo:[0,0,1] neg_hi:[0,0,1]
	v_pk_mul_f32 v[122:123], v[122:123], v[176:177]
	v_pk_fma_f32 v[112:113], v[112:113], v[174:175], v[120:121]
	v_lshlrev_b32_e32 v144, 1, v151
	v_pk_fma_f32 v[126:127], v[114:115], v[176:177], v[126:127] neg_lo:[0,0,1] neg_hi:[0,0,1]
	v_pk_fma_f32 v[114:115], v[114:115], v[172:173], v[122:123]
	v_lshl_add_u64 v[122:123], v[188:189], 0, v[144:145]
	v_cvt_pk_bf16_f32 v112, v112, v113
	v_or_b32_e32 v172, 16, v158
	v_cvt_pk_bf16_f32 v113, v114, v115
	v_mov_b32_e32 v246, v112
	v_mov_b32_e32 v247, v113
	v_lshlrev_b32_e32 v112, 6, v172
	v_cvt_pk_bf16_f32 v120, v184, v185
	v_cvt_pk_bf16_f32 v121, v186, v187
	v_cvt_pk_bf16_f32 v116, v116, v117
	v_cvt_pk_bf16_f32 v117, v118, v119
	v_and_b32_e32 v112, 0x7c0, v112
	v_mov_b32_e32 v113, v145
	v_mov_b32_e32 v248, v120
	v_mov_b32_e32 v249, v121
	v_mov_b32_e32 v250, v116
	v_mov_b32_e32 v251, v117
	v_cvt_pk_bf16_f32 v116, v124, v125
	v_cvt_pk_bf16_f32 v117, v126, v127
	v_mov_b32_e32 v244, v116
	v_mov_b32_e32 v245, v117
	v_and_b32_e32 v242, 16, v190
	v_mul_u32_u24_e32 v242, 3, v242
	v_lshrrev_b32_e32 v242, 1, v242
	v_mov_b32_e32 v243, 0
	v_lshl_add_u64 v[240:241], v[122:123], 0, v[242:243]
	v_permlane16_swap_b32 v248, v250
	v_permlane16_swap_b32 v249, v251
	v_permlane16_swap_b32 v244, v246
	v_permlane16_swap_b32 v245, v247
	flat_store_dwordx4 v[240:241], v[248:251]
	flat_store_dwordx4 v[240:241], v[244:247] offset:64
	v_lshl_add_u64 v[114:115], v[160:161], 0, v[112:113]
	v_lshl_add_u64 v[120:121], v[162:163], 0, v[112:113]
	flat_load_dwordx4 v[116:119], v[168:169]
	flat_load_dwordx4 v[124:127], v[170:171]
	s_nop 0
	flat_load_dwordx4 v[112:115], v[114:115]
	s_nop 0
	flat_load_dwordx4 v[120:123], v[120:121]
	ds_read_b32 v146, v218 offset:64
	v_ashrrev_i32_e32 v173, 31, v172
	s_waitcnt lgkmcnt(0)
	v_pk_mul_f32 v[174:175], v[108:109], v[146:147] op_sel_hi:[1,0]
	s_nop 0
	v_mul_f32_e32 v148, v175, v175
	v_pk_mul_f32 v[110:111], v[110:111], v[146:147] op_sel_hi:[1,0]
	v_fmac_f32_e32 v148, v174, v174
	v_fmac_f32_e32 v148, v110, v110
	v_pk_mul_f32 v[108:109], v[104:105], v[146:147] op_sel_hi:[1,0]
	v_fmac_f32_e32 v148, v111, v111
	v_fmac_f32_e32 v148, v108, v108
	v_pk_mul_f32 v[106:107], v[106:107], v[146:147] op_sel_hi:[1,0]
	v_fmac_f32_e32 v148, v109, v109
	v_pk_mul_f32 v[104:105], v[100:101], v[146:147] op_sel_hi:[1,0]
	v_fmac_f32_e32 v148, v106, v106
	v_pk_mul_f32 v[102:103], v[102:103], v[146:147] op_sel_hi:[1,0]
	v_pk_mul_f32 v[98:99], v[98:99], v[146:147] op_sel_hi:[1,0]
	v_pk_mul_f32 v[100:101], v[96:97], v[146:147] op_sel_hi:[1,0]
	v_fmac_f32_e32 v148, v107, v107
	v_pk_mul_f32 v[146:147], v[104:105], v[104:105]
	v_pk_mul_f32 v[96:97], v[102:103], v[102:103]
	v_add_f32_e32 v146, v146, v148
	v_add_f32_e32 v146, v147, v146
	v_add_f32_e32 v96, v96, v146
	v_add_f32_e32 v148, v97, v96
	v_pk_mul_f32 v[146:147], v[100:101], v[100:101]
	v_pk_mul_f32 v[96:97], v[98:99], v[98:99]
	v_add_f32_e32 v146, v146, v148
	v_add_f32_e32 v146, v147, v146
	v_add_f32_e32 v96, v96, v146
	v_add_f32_e32 v96, v97, v96
	ds_bpermute_b32 v97, v216, v96
	s_waitcnt lgkmcnt(0)
	v_add_f32_e32 v151, v96, v97
	ds_bpermute_b32 v159, v217, v151
	s_and_saveexec_b64 s[2:3], vcc
	s_xor_b64 s[2:3], exec, s[2:3]
	v_lshlrev_b64 v[96:97], 8, v[172:173]
	v_lshl_add_u64 v[96:97], v[156:157], 0, v[96:97]
	s_mov_b64 s[6:7], 0x69dfc00
	v_lshl_add_u64 v[96:97], v[96:97], 0, s[6:7]
	s_andn2_saveexec_b64 s[2:3], s[2:3]
	v_lshlrev_b64 v[96:97], 10, v[172:173]
	v_lshl_add_u64 v[96:97], v[154:155], 0, v[96:97]
	s_or_b64 exec, exec, s[2:3]
	s_waitcnt lgkmcnt(0)
	v_add_f32_e32 v146, v151, v159
	v_fmamk_f32 v146, v146, 0x3c800000, v192
	v_mul_f32_e32 v147, 0x4b800000, v146
	v_cmp_gt_f32_e64 s[6:7], s58, v146
	v_lshl_add_u64 v[96:97], v[96:97], 0, v[144:145]
	s_nop 0
	v_cndmask_b32_e64 v146, v146, v147, s[6:7]
	v_rsq_f32_e32 v146, v146
	s_nop 0
	v_mul_f32_e32 v147, 0x45800000, v146
	v_cndmask_b32_e64 v146, v146, v147, s[6:7]
	v_pk_mul_f32 v[148:149], v[174:175], v[146:147] op_sel_hi:[1,0]
	v_pk_mul_f32 v[108:109], v[108:109], v[146:147] op_sel_hi:[1,0]
	v_pk_mul_f32 v[106:107], v[106:107], v[146:147] op_sel_hi:[1,0]
	v_pk_mul_f32 v[110:111], v[110:111], v[146:147] op_sel_hi:[1,0]
	v_pk_mul_f32 v[148:149], v[140:141], v[148:149]
	v_pk_mul_f32 v[106:107], v[138:139], v[106:107]
	v_pk_mul_f32 v[108:109], v[136:137], v[108:109]
	v_pk_mul_f32 v[98:99], v[98:99], v[146:147] op_sel_hi:[1,0]
	v_pk_mul_f32 v[110:111], v[142:143], v[110:111]
	v_pk_mul_f32 v[102:103], v[102:103], v[146:147] op_sel_hi:[1,0]
	v_pk_mul_f32 v[104:105], v[104:105], v[146:147] op_sel_hi:[1,0]
	v_pk_mul_f32 v[100:101], v[100:101], v[146:147] op_sel_hi:[1,0]
	v_pk_mul_f32 v[98:99], v[130:131], v[98:99]
	s_waitcnt vmcnt(0)
	v_pk_mul_f32 v[146:147], v[124:125], v[108:109]
	v_pk_mul_f32 v[172:173], v[126:127], v[106:107]
	v_pk_mul_f32 v[124:125], v[124:125], v[148:149]
	v_pk_mul_f32 v[102:103], v[134:135], v[102:103]
	v_pk_mul_f32 v[100:101], v[128:129], v[100:101]
	v_pk_fma_f32 v[172:173], v[118:119], v[110:111], v[172:173] neg_lo:[0,0,1] neg_hi:[0,0,1]
	v_pk_fma_f32 v[146:147], v[116:117], v[148:149], v[146:147] neg_lo:[0,0,1] neg_hi:[0,0,1]
	v_pk_mul_f32 v[110:111], v[126:127], v[110:111]
	v_pk_fma_f32 v[108:109], v[116:117], v[108:109], v[124:125]
	v_pk_mul_f32 v[116:117], v[122:123], v[98:99]
	v_pk_mul_f32 v[104:105], v[132:133], v[104:105]
	v_pk_fma_f32 v[106:107], v[118:119], v[106:107], v[110:111]
	v_pk_mul_f32 v[110:111], v[120:121], v[100:101]
	v_pk_fma_f32 v[116:117], v[114:115], v[102:103], v[116:117] neg_lo:[0,0,1] neg_hi:[0,0,1]
	v_pk_mul_f32 v[102:103], v[122:123], v[102:103]
	v_pk_fma_f32 v[110:111], v[112:113], v[104:105], v[110:111] neg_lo:[0,0,1] neg_hi:[0,0,1]
	v_pk_mul_f32 v[104:105], v[120:121], v[104:105]
	v_pk_fma_f32 v[98:99], v[114:115], v[98:99], v[102:103]
	v_cvt_pk_bf16_f32 v102, v146, v147
	v_cvt_pk_bf16_f32 v103, v172, v173
	v_pk_fma_f32 v[100:101], v[112:113], v[100:101], v[104:105]
	v_mov_b32_e32 v248, v102
	v_mov_b32_e32 v249, v103
	v_cvt_pk_bf16_f32 v102, v108, v109
	v_cvt_pk_bf16_f32 v103, v106, v107
	v_or_b32_e32 v112, 32, v158
	v_mov_b32_e32 v250, v102
	v_mov_b32_e32 v251, v103
	v_cvt_pk_bf16_f32 v102, v110, v111
	v_cvt_pk_bf16_f32 v103, v116, v117
	v_mov_b32_e32 v244, v102
	v_mov_b32_e32 v245, v103
	v_cvt_pk_bf16_f32 v100, v100, v101
	v_cvt_pk_bf16_f32 v101, v98, v99
	v_mov_b32_e32 v246, v100
	v_mov_b32_e32 v247, v101
	v_and_b32_e32 v242, 16, v190
	v_mul_u32_u24_e32 v242, 3, v242
	v_lshrrev_b32_e32 v242, 1, v242
	v_mov_b32_e32 v243, 0
	v_lshl_add_u64 v[240:241], v[96:97], 0, v[242:243]
	v_permlane16_swap_b32 v248, v250
	v_permlane16_swap_b32 v249, v251
	v_permlane16_swap_b32 v244, v246
	v_permlane16_swap_b32 v245, v247
	flat_store_dwordx4 v[240:241], v[248:251]
	flat_store_dwordx4 v[240:241], v[244:247] offset:64
	v_lshlrev_b32_e32 v96, 6, v112
	v_and_b32_e32 v96, 0xbc0, v96
	v_mov_b32_e32 v97, v145
	v_lshl_add_u64 v[98:99], v[160:161], 0, v[96:97]
	v_lshl_add_u64 v[104:105], v[162:163], 0, v[96:97]
	flat_load_dwordx4 v[100:103], v[168:169]
	flat_load_dwordx4 v[108:111], v[170:171]
	s_nop 0
	flat_load_dwordx4 v[96:99], v[98:99]
	s_nop 0
	flat_load_dwordx4 v[104:107], v[104:105]
	ds_read_b32 v116, v218 offset:128
	s_waitcnt lgkmcnt(0)
	v_pk_mul_f32 v[114:115], v[92:93], v[116:117] op_sel_hi:[1,0]
	s_nop 0
	v_mul_f32_e32 v113, v115, v115
	v_pk_mul_f32 v[94:95], v[94:95], v[116:117] op_sel_hi:[1,0]
	v_fmac_f32_e32 v113, v114, v114
	v_fmac_f32_e32 v113, v94, v94
	v_pk_mul_f32 v[92:93], v[88:89], v[116:117] op_sel_hi:[1,0]
	v_fmac_f32_e32 v113, v95, v95
	v_fmac_f32_e32 v113, v92, v92
	v_pk_mul_f32 v[90:91], v[90:91], v[116:117] op_sel_hi:[1,0]
	v_fmac_f32_e32 v113, v93, v93
	v_pk_mul_f32 v[88:89], v[84:85], v[116:117] op_sel_hi:[1,0]
	v_fmac_f32_e32 v113, v90, v90
	v_pk_mul_f32 v[86:87], v[86:87], v[116:117] op_sel_hi:[1,0]
	v_pk_mul_f32 v[82:83], v[82:83], v[116:117] op_sel_hi:[1,0]
	v_pk_mul_f32 v[84:85], v[80:81], v[116:117] op_sel_hi:[1,0]
	v_fmac_f32_e32 v113, v91, v91
	v_pk_mul_f32 v[116:117], v[88:89], v[88:89]
	v_pk_mul_f32 v[80:81], v[86:87], v[86:87]
	v_add_f32_e32 v113, v116, v113
	v_add_f32_e32 v113, v117, v113
	v_add_f32_e32 v80, v80, v113
	v_add_f32_e32 v113, v81, v80
	v_pk_mul_f32 v[116:117], v[84:85], v[84:85]
	v_pk_mul_f32 v[80:81], v[82:83], v[82:83]
	v_add_f32_e32 v113, v116, v113
	v_add_f32_e32 v113, v117, v113
	v_add_f32_e32 v80, v80, v113
	v_add_f32_e32 v80, v81, v80
	ds_bpermute_b32 v81, v216, v80
	v_ashrrev_i32_e32 v113, 31, v112
	s_waitcnt lgkmcnt(0)
	v_add_f32_e32 v116, v80, v81
	ds_bpermute_b32 v117, v217, v116
	s_and_saveexec_b64 s[2:3], vcc
	s_xor_b64 s[2:3], exec, s[2:3]
	v_lshlrev_b64 v[80:81], 8, v[112:113]
	v_lshl_add_u64 v[80:81], v[156:157], 0, v[80:81]
	s_mov_b64 s[6:7], 0x69dfc00
	v_lshl_add_u64 v[80:81], v[80:81], 0, s[6:7]
	s_andn2_saveexec_b64 s[2:3], s[2:3]
	v_lshlrev_b64 v[80:81], 10, v[112:113]
	v_lshl_add_u64 v[80:81], v[154:155], 0, v[80:81]
	s_or_b64 exec, exec, s[2:3]
	s_waitcnt lgkmcnt(0)
	v_add_f32_e32 v112, v116, v117
	v_fmamk_f32 v112, v112, 0x3c800000, v192
	v_mul_f32_e32 v113, 0x4b800000, v112
	v_cmp_gt_f32_e64 s[6:7], s58, v112
	v_lshl_add_u64 v[80:81], v[80:81], 0, v[144:145]
	s_nop 0
	v_cndmask_b32_e64 v112, v112, v113, s[6:7]
	v_rsq_f32_e32 v112, v112
	s_nop 0
	v_mul_f32_e32 v113, 0x45800000, v112
	v_cndmask_b32_e64 v112, v112, v113, s[6:7]
	v_pk_mul_f32 v[114:115], v[114:115], v[112:113] op_sel_hi:[1,0]
	v_pk_mul_f32 v[92:93], v[92:93], v[112:113] op_sel_hi:[1,0]
	v_pk_mul_f32 v[90:91], v[90:91], v[112:113] op_sel_hi:[1,0]
	v_pk_mul_f32 v[94:95], v[94:95], v[112:113] op_sel_hi:[1,0]
	v_pk_mul_f32 v[114:115], v[140:141], v[114:115]
	v_pk_mul_f32 v[90:91], v[138:139], v[90:91]
	v_pk_mul_f32 v[92:93], v[136:137], v[92:93]
	v_pk_mul_f32 v[82:83], v[82:83], v[112:113] op_sel_hi:[1,0]
	v_pk_mul_f32 v[94:95], v[142:143], v[94:95]
	v_pk_mul_f32 v[86:87], v[86:87], v[112:113] op_sel_hi:[1,0]
	v_pk_mul_f32 v[88:89], v[88:89], v[112:113] op_sel_hi:[1,0]
	v_pk_mul_f32 v[84:85], v[84:85], v[112:113] op_sel_hi:[1,0]
	v_pk_mul_f32 v[82:83], v[130:131], v[82:83]
	s_waitcnt vmcnt(0)
	v_pk_mul_f32 v[112:113], v[108:109], v[92:93]
	v_pk_mul_f32 v[116:117], v[110:111], v[90:91]
	v_pk_mul_f32 v[108:109], v[108:109], v[114:115]
	v_pk_mul_f32 v[86:87], v[134:135], v[86:87]
	v_pk_mul_f32 v[84:85], v[128:129], v[84:85]
	v_pk_fma_f32 v[116:117], v[102:103], v[94:95], v[116:117] neg_lo:[0,0,1] neg_hi:[0,0,1]
	v_pk_fma_f32 v[112:113], v[100:101], v[114:115], v[112:113] neg_lo:[0,0,1] neg_hi:[0,0,1]
	v_pk_mul_f32 v[94:95], v[110:111], v[94:95]
	v_pk_fma_f32 v[92:93], v[100:101], v[92:93], v[108:109]
	v_pk_mul_f32 v[100:101], v[106:107], v[82:83]
	v_pk_mul_f32 v[88:89], v[132:133], v[88:89]
	v_pk_fma_f32 v[90:91], v[102:103], v[90:91], v[94:95]
	v_pk_mul_f32 v[94:95], v[104:105], v[84:85]
	v_pk_fma_f32 v[100:101], v[98:99], v[86:87], v[100:101] neg_lo:[0,0,1] neg_hi:[0,0,1]
	v_pk_mul_f32 v[86:87], v[106:107], v[86:87]
	v_pk_fma_f32 v[94:95], v[96:97], v[88:89], v[94:95] neg_lo:[0,0,1] neg_hi:[0,0,1]
	v_pk_mul_f32 v[88:89], v[104:105], v[88:89]
	v_pk_fma_f32 v[82:83], v[98:99], v[82:83], v[86:87]
	v_cvt_pk_bf16_f32 v86, v112, v113
	v_cvt_pk_bf16_f32 v87, v116, v117
	v_pk_fma_f32 v[84:85], v[96:97], v[84:85], v[88:89]
	v_mov_b32_e32 v248, v86
	v_mov_b32_e32 v249, v87
	v_cvt_pk_bf16_f32 v86, v92, v93
	v_cvt_pk_bf16_f32 v87, v90, v91
	v_or_b32_e32 v96, 48, v158
	v_mov_b32_e32 v250, v86
	v_mov_b32_e32 v251, v87
	v_cvt_pk_bf16_f32 v86, v94, v95
	v_cvt_pk_bf16_f32 v87, v100, v101
	v_mov_b32_e32 v244, v86
	v_mov_b32_e32 v245, v87
	v_cvt_pk_bf16_f32 v84, v84, v85
	v_cvt_pk_bf16_f32 v85, v82, v83
	v_mov_b32_e32 v246, v84
	v_mov_b32_e32 v247, v85
	v_and_b32_e32 v242, 16, v190
	v_mul_u32_u24_e32 v242, 3, v242
	v_lshrrev_b32_e32 v242, 1, v242
	v_mov_b32_e32 v243, 0
	v_lshl_add_u64 v[240:241], v[80:81], 0, v[242:243]
	v_permlane16_swap_b32 v248, v250
	v_permlane16_swap_b32 v249, v251
	v_permlane16_swap_b32 v244, v246
	v_permlane16_swap_b32 v245, v247
	flat_store_dwordx4 v[240:241], v[248:251]
	flat_store_dwordx4 v[240:241], v[244:247] offset:64
	v_lshlrev_b32_e32 v80, 6, v96
	v_and_b32_e32 v80, 0xfc0, v80
	v_mov_b32_e32 v81, v145
	v_lshl_add_u64 v[82:83], v[160:161], 0, v[80:81]
	v_lshl_add_u64 v[88:89], v[162:163], 0, v[80:81]
	flat_load_dwordx4 v[84:87], v[168:169]
	flat_load_dwordx4 v[92:95], v[170:171]
	s_nop 0
	flat_load_dwordx4 v[80:83], v[82:83]
	s_nop 0
	flat_load_dwordx4 v[88:91], v[88:89]
	ds_read_b32 v100, v218 offset:192
	s_waitcnt lgkmcnt(0)
	v_pk_mul_f32 v[98:99], v[76:77], v[100:101] op_sel_hi:[1,0]
	s_nop 0
	v_mul_f32_e32 v97, v99, v99
	v_pk_mul_f32 v[78:79], v[78:79], v[100:101] op_sel_hi:[1,0]
	v_fmac_f32_e32 v97, v98, v98
	v_fmac_f32_e32 v97, v78, v78
	v_pk_mul_f32 v[76:77], v[72:73], v[100:101] op_sel_hi:[1,0]
	v_fmac_f32_e32 v97, v79, v79
	v_fmac_f32_e32 v97, v76, v76
	v_pk_mul_f32 v[74:75], v[74:75], v[100:101] op_sel_hi:[1,0]
	v_fmac_f32_e32 v97, v77, v77
	v_pk_mul_f32 v[72:73], v[68:69], v[100:101] op_sel_hi:[1,0]
	v_fmac_f32_e32 v97, v74, v74
	v_pk_mul_f32 v[70:71], v[70:71], v[100:101] op_sel_hi:[1,0]
	v_pk_mul_f32 v[66:67], v[66:67], v[100:101] op_sel_hi:[1,0]
	v_pk_mul_f32 v[68:69], v[64:65], v[100:101] op_sel_hi:[1,0]
	v_fmac_f32_e32 v97, v75, v75
	v_pk_mul_f32 v[100:101], v[72:73], v[72:73]
	v_pk_mul_f32 v[64:65], v[70:71], v[70:71]
	v_add_f32_e32 v97, v100, v97
	v_add_f32_e32 v97, v101, v97
	v_add_f32_e32 v64, v64, v97
	v_add_f32_e32 v97, v65, v64
	v_pk_mul_f32 v[100:101], v[68:69], v[68:69]
	v_pk_mul_f32 v[64:65], v[66:67], v[66:67]
	v_add_f32_e32 v97, v100, v97
	v_add_f32_e32 v97, v101, v97
	v_add_f32_e32 v64, v64, v97
	v_add_f32_e32 v64, v65, v64
	ds_bpermute_b32 v65, v216, v64
	v_ashrrev_i32_e32 v97, 31, v96
	s_waitcnt lgkmcnt(0)
	v_add_f32_e32 v100, v64, v65
	ds_bpermute_b32 v101, v217, v100
	s_and_saveexec_b64 s[2:3], vcc
	s_xor_b64 s[2:3], exec, s[2:3]
	v_lshlrev_b64 v[64:65], 8, v[96:97]
	v_lshl_add_u64 v[64:65], v[156:157], 0, v[64:65]
	s_mov_b64 s[6:7], 0x69dfc00
	v_lshl_add_u64 v[64:65], v[64:65], 0, s[6:7]
	s_andn2_saveexec_b64 s[2:3], s[2:3]
	v_lshlrev_b64 v[64:65], 10, v[96:97]
	v_lshl_add_u64 v[64:65], v[154:155], 0, v[64:65]
	s_or_b64 exec, exec, s[2:3]
	s_waitcnt lgkmcnt(0)
	v_add_f32_e32 v96, v100, v101
	v_fmamk_f32 v96, v96, 0x3c800000, v192
	v_mul_f32_e32 v97, 0x4b800000, v96
	v_cmp_gt_f32_e64 s[6:7], s58, v96
	v_lshl_add_u64 v[64:65], v[64:65], 0, v[144:145]
	s_movk_i32 s0, 0xfc0
	v_cndmask_b32_e64 v96, v96, v97, s[6:7]
	v_rsq_f32_e32 v96, v96
	s_nop 0
	v_mul_f32_e32 v97, 0x45800000, v96
	v_cndmask_b32_e64 v96, v96, v97, s[6:7]
	v_pk_mul_f32 v[98:99], v[98:99], v[96:97] op_sel_hi:[1,0]
	v_pk_mul_f32 v[76:77], v[76:77], v[96:97] op_sel_hi:[1,0]
	v_pk_mul_f32 v[74:75], v[74:75], v[96:97] op_sel_hi:[1,0]
	v_pk_mul_f32 v[78:79], v[78:79], v[96:97] op_sel_hi:[1,0]
	v_pk_mul_f32 v[98:99], v[140:141], v[98:99]
	v_pk_mul_f32 v[74:75], v[138:139], v[74:75]
	v_pk_mul_f32 v[76:77], v[136:137], v[76:77]
	v_pk_mul_f32 v[66:67], v[66:67], v[96:97] op_sel_hi:[1,0]
	v_pk_mul_f32 v[78:79], v[142:143], v[78:79]
	v_pk_mul_f32 v[70:71], v[70:71], v[96:97] op_sel_hi:[1,0]
	v_pk_mul_f32 v[72:73], v[72:73], v[96:97] op_sel_hi:[1,0]
	v_pk_mul_f32 v[68:69], v[68:69], v[96:97] op_sel_hi:[1,0]
	v_pk_mul_f32 v[66:67], v[130:131], v[66:67]
	s_waitcnt vmcnt(0)
	v_pk_mul_f32 v[96:97], v[92:93], v[76:77]
	v_pk_mul_f32 v[100:101], v[94:95], v[74:75]
	v_pk_mul_f32 v[92:93], v[92:93], v[98:99]
	v_pk_mul_f32 v[70:71], v[134:135], v[70:71]
	v_pk_mul_f32 v[68:69], v[128:129], v[68:69]
	v_pk_fma_f32 v[100:101], v[86:87], v[78:79], v[100:101] neg_lo:[0,0,1] neg_hi:[0,0,1]
	v_pk_fma_f32 v[96:97], v[84:85], v[98:99], v[96:97] neg_lo:[0,0,1] neg_hi:[0,0,1]
	v_pk_mul_f32 v[78:79], v[94:95], v[78:79]
	v_pk_fma_f32 v[76:77], v[84:85], v[76:77], v[92:93]
	v_pk_mul_f32 v[84:85], v[90:91], v[66:67]
	v_pk_mul_f32 v[72:73], v[132:133], v[72:73]
	v_pk_fma_f32 v[74:75], v[86:87], v[74:75], v[78:79]
	v_pk_mul_f32 v[78:79], v[88:89], v[68:69]
	v_pk_fma_f32 v[84:85], v[82:83], v[70:71], v[84:85] neg_lo:[0,0,1] neg_hi:[0,0,1]
	v_pk_mul_f32 v[70:71], v[90:91], v[70:71]
	v_pk_fma_f32 v[78:79], v[80:81], v[72:73], v[78:79] neg_lo:[0,0,1] neg_hi:[0,0,1]
	v_pk_mul_f32 v[72:73], v[88:89], v[72:73]
	v_pk_fma_f32 v[66:67], v[82:83], v[66:67], v[70:71]
	v_cvt_pk_bf16_f32 v70, v96, v97
	v_cvt_pk_bf16_f32 v71, v100, v101
	v_pk_fma_f32 v[68:69], v[80:81], v[68:69], v[72:73]
	v_mov_b32_e32 v248, v70
	v_mov_b32_e32 v249, v71
	v_cvt_pk_bf16_f32 v70, v76, v77
	v_cvt_pk_bf16_f32 v71, v74, v75
	v_mov_b32_e32 v250, v70
	v_mov_b32_e32 v251, v71
	v_cvt_pk_bf16_f32 v70, v78, v79
	v_cvt_pk_bf16_f32 v71, v84, v85
	v_mov_b32_e32 v244, v70
	v_mov_b32_e32 v245, v71
	v_cvt_pk_bf16_f32 v68, v68, v69
	v_cvt_pk_bf16_f32 v69, v66, v67
	v_mov_b32_e32 v246, v68
	v_mov_b32_e32 v247, v69
	v_and_b32_e32 v242, 16, v190
	v_mul_u32_u24_e32 v242, 3, v242
	v_lshrrev_b32_e32 v242, 1, v242
	v_mov_b32_e32 v243, 0
	v_lshl_add_u64 v[240:241], v[64:65], 0, v[242:243]
	v_permlane16_swap_b32 v248, v250
	v_permlane16_swap_b32 v249, v251
	v_permlane16_swap_b32 v244, v246
	v_permlane16_swap_b32 v245, v247
	flat_store_dwordx4 v[240:241], v[248:251]
	flat_store_dwordx4 v[240:241], v[244:247] offset:64
	v_bitop3_b32 v64, v158, s0, 64 bitop3:0xc8
	v_mov_b32_e32 v65, v145
	v_lshl_add_u64 v[66:67], v[160:161], 0, v[64:65]
	v_lshl_add_u64 v[64:65], v[162:163], 0, v[64:65]
	flat_load_dwordx4 v[72:75], v[66:67]
	flat_load_dwordx4 v[76:79], v[64:65]
	s_nop 0
	flat_load_dwordx4 v[64:67], v[164:165]
	flat_load_dwordx4 v[68:71], v[166:167]
	ds_read_b32 v82, v218 offset:256
	s_waitcnt lgkmcnt(0)
	v_pk_mul_f32 v[80:81], v[60:61], v[82:83] op_sel_hi:[1,0]
	s_nop 0
	v_mul_f32_e32 v84, v81, v81
	v_pk_mul_f32 v[62:63], v[62:63], v[82:83] op_sel_hi:[1,0]
	v_fmac_f32_e32 v84, v80, v80
	v_fmac_f32_e32 v84, v62, v62
	v_pk_mul_f32 v[60:61], v[56:57], v[82:83] op_sel_hi:[1,0]
	v_fmac_f32_e32 v84, v63, v63
	v_fmac_f32_e32 v84, v60, v60
	v_pk_mul_f32 v[58:59], v[58:59], v[82:83] op_sel_hi:[1,0]
	v_fmac_f32_e32 v84, v61, v61
	v_pk_mul_f32 v[56:57], v[52:53], v[82:83] op_sel_hi:[1,0]
	v_fmac_f32_e32 v84, v58, v58
	v_pk_mul_f32 v[54:55], v[54:55], v[82:83] op_sel_hi:[1,0]
	v_pk_mul_f32 v[50:51], v[50:51], v[82:83] op_sel_hi:[1,0]
	v_pk_mul_f32 v[52:53], v[48:49], v[82:83] op_sel_hi:[1,0]
	v_fmac_f32_e32 v84, v59, v59
	v_pk_mul_f32 v[82:83], v[56:57], v[56:57]
	v_pk_mul_f32 v[48:49], v[54:55], v[54:55]
	v_add_f32_e32 v82, v82, v84
	v_add_f32_e32 v82, v83, v82
	v_add_f32_e32 v48, v48, v82
	v_add_f32_e32 v84, v49, v48
	v_pk_mul_f32 v[82:83], v[52:53], v[52:53]
	v_pk_mul_f32 v[48:49], v[50:51], v[50:51]
	v_add_f32_e32 v82, v82, v84
	v_add_f32_e32 v82, v83, v82
	v_add_f32_e32 v48, v48, v82
	v_add_f32_e32 v48, v49, v48
	ds_bpermute_b32 v49, v216, v48
	v_or_b32_e32 v82, 64, v158
	v_ashrrev_i32_e32 v83, 31, v82
	s_waitcnt lgkmcnt(0)
	v_add_f32_e32 v84, v48, v49
	ds_bpermute_b32 v85, v217, v84
	s_and_saveexec_b64 s[2:3], vcc
	s_xor_b64 s[2:3], exec, s[2:3]
	v_lshlrev_b64 v[48:49], 8, v[82:83]
	v_lshl_add_u64 v[48:49], v[156:157], 0, v[48:49]
	s_mov_b64 s[6:7], 0x69dfc00
	v_lshl_add_u64 v[48:49], v[48:49], 0, s[6:7]
	s_andn2_saveexec_b64 s[2:3], s[2:3]
	v_lshlrev_b64 v[48:49], 10, v[82:83]
	v_lshl_add_u64 v[48:49], v[154:155], 0, v[48:49]
	s_or_b64 exec, exec, s[2:3]
	s_waitcnt lgkmcnt(0)
	v_add_f32_e32 v82, v84, v85
	v_fmamk_f32 v82, v82, 0x3c800000, v192
	v_mul_f32_e32 v83, 0x4b800000, v82
	v_cmp_gt_f32_e64 s[6:7], s58, v82
	v_lshl_add_u64 v[48:49], v[48:49], 0, v[144:145]
	s_nop 0
	v_cndmask_b32_e64 v82, v82, v83, s[6:7]
	v_rsq_f32_e32 v82, v82
	s_nop 0
	v_mul_f32_e32 v83, 0x45800000, v82
	v_cndmask_b32_e64 v82, v82, v83, s[6:7]
	v_pk_mul_f32 v[80:81], v[80:81], v[82:83] op_sel_hi:[1,0]
	v_pk_mul_f32 v[60:61], v[60:61], v[82:83] op_sel_hi:[1,0]
	v_pk_mul_f32 v[58:59], v[58:59], v[82:83] op_sel_hi:[1,0]
	v_pk_mul_f32 v[62:63], v[62:63], v[82:83] op_sel_hi:[1,0]
	v_pk_mul_f32 v[80:81], v[140:141], v[80:81]
	v_pk_mul_f32 v[58:59], v[138:139], v[58:59]
	v_pk_mul_f32 v[60:61], v[136:137], v[60:61]
	v_pk_mul_f32 v[50:51], v[50:51], v[82:83] op_sel_hi:[1,0]
	v_pk_mul_f32 v[62:63], v[142:143], v[62:63]
	v_pk_mul_f32 v[54:55], v[54:55], v[82:83] op_sel_hi:[1,0]
	v_pk_mul_f32 v[56:57], v[56:57], v[82:83] op_sel_hi:[1,0]
	v_pk_mul_f32 v[52:53], v[52:53], v[82:83] op_sel_hi:[1,0]
	v_pk_mul_f32 v[50:51], v[130:131], v[50:51]
	s_waitcnt vmcnt(0)
	v_pk_mul_f32 v[82:83], v[76:77], v[60:61]
	v_pk_mul_f32 v[84:85], v[78:79], v[58:59]
	v_pk_mul_f32 v[76:77], v[76:77], v[80:81]
	v_pk_mul_f32 v[54:55], v[134:135], v[54:55]
	v_pk_mul_f32 v[52:53], v[128:129], v[52:53]
	v_pk_fma_f32 v[84:85], v[74:75], v[62:63], v[84:85] neg_lo:[0,0,1] neg_hi:[0,0,1]
	v_pk_fma_f32 v[82:83], v[72:73], v[80:81], v[82:83] neg_lo:[0,0,1] neg_hi:[0,0,1]
	v_pk_mul_f32 v[62:63], v[78:79], v[62:63]
	v_pk_fma_f32 v[60:61], v[72:73], v[60:61], v[76:77]
	v_pk_mul_f32 v[72:73], v[70:71], v[50:51]
	v_pk_mul_f32 v[56:57], v[132:133], v[56:57]
	v_pk_fma_f32 v[58:59], v[74:75], v[58:59], v[62:63]
	v_pk_mul_f32 v[62:63], v[68:69], v[52:53]
	v_pk_fma_f32 v[72:73], v[66:67], v[54:55], v[72:73] neg_lo:[0,0,1] neg_hi:[0,0,1]
	v_pk_mul_f32 v[54:55], v[70:71], v[54:55]
	v_pk_fma_f32 v[62:63], v[64:65], v[56:57], v[62:63] neg_lo:[0,0,1] neg_hi:[0,0,1]
	v_pk_mul_f32 v[56:57], v[68:69], v[56:57]
	v_pk_fma_f32 v[50:51], v[66:67], v[50:51], v[54:55]
	v_cvt_pk_bf16_f32 v54, v82, v83
	v_cvt_pk_bf16_f32 v55, v84, v85
	v_pk_fma_f32 v[52:53], v[64:65], v[52:53], v[56:57]
	v_mov_b32_e32 v248, v54
	v_mov_b32_e32 v249, v55
	v_cvt_pk_bf16_f32 v54, v60, v61
	v_cvt_pk_bf16_f32 v55, v58, v59
	v_mov_b32_e32 v250, v54
	v_mov_b32_e32 v251, v55
	v_cvt_pk_bf16_f32 v54, v62, v63
	v_cvt_pk_bf16_f32 v55, v72, v73
	v_mov_b32_e32 v244, v54
	v_mov_b32_e32 v245, v55
	v_cvt_pk_bf16_f32 v52, v52, v53
	v_cvt_pk_bf16_f32 v53, v50, v51
	v_mov_b32_e32 v246, v52
	v_mov_b32_e32 v247, v53
	v_and_b32_e32 v242, 16, v190
	v_mul_u32_u24_e32 v242, 3, v242
	v_lshrrev_b32_e32 v242, 1, v242
	v_mov_b32_e32 v243, 0
	v_lshl_add_u64 v[240:241], v[48:49], 0, v[242:243]
	v_permlane16_swap_b32 v248, v250
	v_permlane16_swap_b32 v249, v251
	v_permlane16_swap_b32 v244, v246
	v_permlane16_swap_b32 v245, v247
	flat_store_dwordx4 v[240:241], v[248:251]
	flat_store_dwordx4 v[240:241], v[244:247] offset:64
	v_bitop3_b32 v48, v158, s0, v211 bitop3:0xc8
	v_mov_b32_e32 v49, v145
	v_or_b32_e32 v64, 0x50, v158
	v_lshl_add_u64 v[50:51], v[160:161], 0, v[48:49]
	v_lshl_add_u64 v[48:49], v[162:163], 0, v[48:49]
	flat_load_dwordx4 v[52:55], v[50:51]
	flat_load_dwordx4 v[60:63], v[48:49]
	v_lshlrev_b32_e32 v48, 6, v64
	v_and_b32_e32 v48, 0x7c0, v48
	v_mov_b32_e32 v49, v145
	v_lshl_add_u64 v[50:51], v[160:161], 0, v[48:49]
	v_lshl_add_u64 v[56:57], v[162:163], 0, v[48:49]
	flat_load_dwordx4 v[48:51], v[50:51]
	s_nop 0
	flat_load_dwordx4 v[56:59], v[56:57]
	ds_read_b32 v68, v218 offset:320
	s_waitcnt lgkmcnt(0)
	v_pk_mul_f32 v[66:67], v[44:45], v[68:69] op_sel_hi:[1,0]
	s_nop 0
	v_mul_f32_e32 v65, v67, v67
	v_pk_mul_f32 v[46:47], v[46:47], v[68:69] op_sel_hi:[1,0]
	v_fmac_f32_e32 v65, v66, v66
	v_fmac_f32_e32 v65, v46, v46
	v_pk_mul_f32 v[44:45], v[40:41], v[68:69] op_sel_hi:[1,0]
	v_fmac_f32_e32 v65, v47, v47
	v_fmac_f32_e32 v65, v44, v44
	v_pk_mul_f32 v[42:43], v[42:43], v[68:69] op_sel_hi:[1,0]
	v_fmac_f32_e32 v65, v45, v45
	v_pk_mul_f32 v[40:41], v[36:37], v[68:69] op_sel_hi:[1,0]
	v_fmac_f32_e32 v65, v42, v42
	v_pk_mul_f32 v[38:39], v[38:39], v[68:69] op_sel_hi:[1,0]
	v_pk_mul_f32 v[34:35], v[34:35], v[68:69] op_sel_hi:[1,0]
	v_pk_mul_f32 v[36:37], v[32:33], v[68:69] op_sel_hi:[1,0]
	v_fmac_f32_e32 v65, v43, v43
	v_pk_mul_f32 v[68:69], v[40:41], v[40:41]
	v_pk_mul_f32 v[32:33], v[38:39], v[38:39]
	v_add_f32_e32 v65, v68, v65
	v_add_f32_e32 v65, v69, v65
	v_add_f32_e32 v32, v32, v65
	v_add_f32_e32 v65, v33, v32
	v_pk_mul_f32 v[68:69], v[36:37], v[36:37]
	v_pk_mul_f32 v[32:33], v[34:35], v[34:35]
	v_add_f32_e32 v65, v68, v65
	v_add_f32_e32 v65, v69, v65
	v_add_f32_e32 v32, v32, v65
	v_add_f32_e32 v32, v33, v32
	ds_bpermute_b32 v33, v216, v32
	v_ashrrev_i32_e32 v65, 31, v64
	s_waitcnt lgkmcnt(0)
	v_add_f32_e32 v68, v32, v33
	ds_bpermute_b32 v69, v217, v68
	s_and_saveexec_b64 s[2:3], vcc
	s_xor_b64 s[2:3], exec, s[2:3]
	v_lshlrev_b64 v[32:33], 8, v[64:65]
	v_lshl_add_u64 v[32:33], v[156:157], 0, v[32:33]
	s_mov_b64 s[6:7], 0x69dfc00
	v_lshl_add_u64 v[32:33], v[32:33], 0, s[6:7]
	s_andn2_saveexec_b64 s[2:3], s[2:3]
	v_lshlrev_b64 v[32:33], 10, v[64:65]
	v_lshl_add_u64 v[32:33], v[154:155], 0, v[32:33]
	s_or_b64 exec, exec, s[2:3]
	s_waitcnt lgkmcnt(0)
	v_add_f32_e32 v64, v68, v69
	v_fmamk_f32 v64, v64, 0x3c800000, v192
	v_mul_f32_e32 v65, 0x4b800000, v64
	v_cmp_gt_f32_e64 s[6:7], s58, v64
	v_lshl_add_u64 v[32:33], v[32:33], 0, v[144:145]
	s_nop 0
	v_cndmask_b32_e64 v64, v64, v65, s[6:7]
	v_rsq_f32_e32 v64, v64
	s_nop 0
	v_mul_f32_e32 v65, 0x45800000, v64
	v_cndmask_b32_e64 v64, v64, v65, s[6:7]
	v_pk_mul_f32 v[66:67], v[66:67], v[64:65] op_sel_hi:[1,0]
	v_pk_mul_f32 v[44:45], v[44:45], v[64:65] op_sel_hi:[1,0]
	v_pk_mul_f32 v[42:43], v[42:43], v[64:65] op_sel_hi:[1,0]
	v_pk_mul_f32 v[46:47], v[46:47], v[64:65] op_sel_hi:[1,0]
	v_pk_mul_f32 v[66:67], v[140:141], v[66:67]
	v_pk_mul_f32 v[42:43], v[138:139], v[42:43]
	v_pk_mul_f32 v[44:45], v[136:137], v[44:45]
	v_pk_mul_f32 v[34:35], v[34:35], v[64:65] op_sel_hi:[1,0]
	v_pk_mul_f32 v[46:47], v[142:143], v[46:47]
	v_pk_mul_f32 v[38:39], v[38:39], v[64:65] op_sel_hi:[1,0]
	v_pk_mul_f32 v[40:41], v[40:41], v[64:65] op_sel_hi:[1,0]
	v_pk_mul_f32 v[36:37], v[36:37], v[64:65] op_sel_hi:[1,0]
	v_pk_mul_f32 v[34:35], v[130:131], v[34:35]
	s_waitcnt vmcnt(0)
	v_pk_mul_f32 v[64:65], v[60:61], v[44:45]
	v_pk_mul_f32 v[68:69], v[62:63], v[42:43]
	v_pk_mul_f32 v[60:61], v[60:61], v[66:67]
	v_pk_mul_f32 v[38:39], v[134:135], v[38:39]
	v_pk_mul_f32 v[36:37], v[128:129], v[36:37]
	v_pk_fma_f32 v[68:69], v[54:55], v[46:47], v[68:69] neg_lo:[0,0,1] neg_hi:[0,0,1]
	v_pk_fma_f32 v[64:65], v[52:53], v[66:67], v[64:65] neg_lo:[0,0,1] neg_hi:[0,0,1]
	v_pk_mul_f32 v[46:47], v[62:63], v[46:47]
	v_pk_fma_f32 v[44:45], v[52:53], v[44:45], v[60:61]
	v_pk_mul_f32 v[52:53], v[58:59], v[34:35]
	v_pk_mul_f32 v[40:41], v[132:133], v[40:41]
	v_pk_fma_f32 v[42:43], v[54:55], v[42:43], v[46:47]
	v_pk_mul_f32 v[46:47], v[56:57], v[36:37]
	v_pk_fma_f32 v[52:53], v[50:51], v[38:39], v[52:53] neg_lo:[0,0,1] neg_hi:[0,0,1]
	v_pk_mul_f32 v[38:39], v[58:59], v[38:39]
	v_pk_fma_f32 v[46:47], v[48:49], v[40:41], v[46:47] neg_lo:[0,0,1] neg_hi:[0,0,1]
	v_pk_mul_f32 v[40:41], v[56:57], v[40:41]
	v_pk_fma_f32 v[34:35], v[50:51], v[34:35], v[38:39]
	v_cvt_pk_bf16_f32 v38, v64, v65
	v_cvt_pk_bf16_f32 v39, v68, v69
	v_pk_fma_f32 v[36:37], v[48:49], v[36:37], v[40:41]
	v_mov_b32_e32 v248, v38
	v_mov_b32_e32 v249, v39
	v_cvt_pk_bf16_f32 v38, v44, v45
	v_cvt_pk_bf16_f32 v39, v42, v43
	v_mov_b32_e32 v250, v38
	v_mov_b32_e32 v251, v39
	v_cvt_pk_bf16_f32 v38, v46, v47
	v_cvt_pk_bf16_f32 v39, v52, v53
	v_mov_b32_e32 v244, v38
	v_mov_b32_e32 v245, v39
	v_cvt_pk_bf16_f32 v36, v36, v37
	v_cvt_pk_bf16_f32 v37, v34, v35
	v_mov_b32_e32 v246, v36
	v_mov_b32_e32 v247, v37
	v_and_b32_e32 v242, 16, v190
	v_mul_u32_u24_e32 v242, 3, v242
	v_lshrrev_b32_e32 v242, 1, v242
	v_mov_b32_e32 v243, 0
	v_lshl_add_u64 v[240:241], v[32:33], 0, v[242:243]
	v_permlane16_swap_b32 v248, v250
	v_permlane16_swap_b32 v249, v251
	v_permlane16_swap_b32 v244, v246
	v_permlane16_swap_b32 v245, v247
	flat_store_dwordx4 v[240:241], v[248:251]
	flat_store_dwordx4 v[240:241], v[244:247] offset:64
	v_bitop3_b32 v32, v158, s0, v212 bitop3:0xc8
	v_mov_b32_e32 v33, v145
	v_or_b32_e32 v48, 0x60, v158
	v_lshl_add_u64 v[34:35], v[160:161], 0, v[32:33]
	v_lshl_add_u64 v[32:33], v[162:163], 0, v[32:33]
	flat_load_dwordx4 v[36:39], v[34:35]
	flat_load_dwordx4 v[44:47], v[32:33]
	v_lshlrev_b32_e32 v32, 6, v48
	v_and_b32_e32 v32, 0xbc0, v32
	v_mov_b32_e32 v33, v145
	v_lshl_add_u64 v[34:35], v[160:161], 0, v[32:33]
	v_lshl_add_u64 v[40:41], v[162:163], 0, v[32:33]
	flat_load_dwordx4 v[32:35], v[34:35]
	s_nop 0
	flat_load_dwordx4 v[40:43], v[40:41]
	ds_read_b32 v52, v218 offset:384
	s_waitcnt lgkmcnt(0)
	v_pk_mul_f32 v[50:51], v[28:29], v[52:53] op_sel_hi:[1,0]
	s_nop 0
	v_mul_f32_e32 v49, v51, v51
	v_pk_mul_f32 v[30:31], v[30:31], v[52:53] op_sel_hi:[1,0]
	v_fmac_f32_e32 v49, v50, v50
	v_fmac_f32_e32 v49, v30, v30
	v_pk_mul_f32 v[28:29], v[24:25], v[52:53] op_sel_hi:[1,0]
	v_fmac_f32_e32 v49, v31, v31
	v_fmac_f32_e32 v49, v28, v28
	v_pk_mul_f32 v[26:27], v[26:27], v[52:53] op_sel_hi:[1,0]
	v_fmac_f32_e32 v49, v29, v29
	v_pk_mul_f32 v[24:25], v[20:21], v[52:53] op_sel_hi:[1,0]
	v_fmac_f32_e32 v49, v26, v26
	v_pk_mul_f32 v[22:23], v[22:23], v[52:53] op_sel_hi:[1,0]
	v_pk_mul_f32 v[18:19], v[18:19], v[52:53] op_sel_hi:[1,0]
	v_pk_mul_f32 v[20:21], v[16:17], v[52:53] op_sel_hi:[1,0]
	v_fmac_f32_e32 v49, v27, v27
	v_pk_mul_f32 v[52:53], v[24:25], v[24:25]
	v_pk_mul_f32 v[16:17], v[22:23], v[22:23]
	v_add_f32_e32 v49, v52, v49
	v_add_f32_e32 v49, v53, v49
	v_add_f32_e32 v16, v16, v49
	v_add_f32_e32 v49, v17, v16
	v_pk_mul_f32 v[52:53], v[20:21], v[20:21]
	v_pk_mul_f32 v[16:17], v[18:19], v[18:19]
	v_add_f32_e32 v49, v52, v49
	v_add_f32_e32 v49, v53, v49
	v_add_f32_e32 v16, v16, v49
	v_add_f32_e32 v16, v17, v16
	ds_bpermute_b32 v17, v216, v16
	v_ashrrev_i32_e32 v49, 31, v48
	s_waitcnt lgkmcnt(0)
	v_add_f32_e32 v52, v16, v17
	ds_bpermute_b32 v53, v217, v52
	s_and_saveexec_b64 s[2:3], vcc
	s_xor_b64 s[2:3], exec, s[2:3]
	v_lshlrev_b64 v[16:17], 8, v[48:49]
	v_lshl_add_u64 v[16:17], v[156:157], 0, v[16:17]
	s_mov_b64 s[6:7], 0x69dfc00
	v_lshl_add_u64 v[16:17], v[16:17], 0, s[6:7]
	s_andn2_saveexec_b64 s[2:3], s[2:3]
	v_lshlrev_b64 v[16:17], 10, v[48:49]
	v_lshl_add_u64 v[16:17], v[154:155], 0, v[16:17]
	s_or_b64 exec, exec, s[2:3]
	s_waitcnt lgkmcnt(0)
	v_add_f32_e32 v48, v52, v53
	v_fmamk_f32 v48, v48, 0x3c800000, v192
	v_mul_f32_e32 v49, 0x4b800000, v48
	v_cmp_gt_f32_e64 s[6:7], s58, v48
	v_lshl_add_u64 v[16:17], v[16:17], 0, v[144:145]
	s_nop 0
	v_cndmask_b32_e64 v48, v48, v49, s[6:7]
	v_rsq_f32_e32 v48, v48
	s_nop 0
	v_mul_f32_e32 v49, 0x45800000, v48
	v_cndmask_b32_e64 v48, v48, v49, s[6:7]
	v_pk_mul_f32 v[50:51], v[50:51], v[48:49] op_sel_hi:[1,0]
	v_pk_mul_f32 v[28:29], v[28:29], v[48:49] op_sel_hi:[1,0]
	v_pk_mul_f32 v[26:27], v[26:27], v[48:49] op_sel_hi:[1,0]
	v_pk_mul_f32 v[30:31], v[30:31], v[48:49] op_sel_hi:[1,0]
	v_pk_mul_f32 v[50:51], v[140:141], v[50:51]
	v_pk_mul_f32 v[26:27], v[138:139], v[26:27]
	v_pk_mul_f32 v[28:29], v[136:137], v[28:29]
	v_pk_mul_f32 v[18:19], v[18:19], v[48:49] op_sel_hi:[1,0]
	v_pk_mul_f32 v[30:31], v[142:143], v[30:31]
	v_pk_mul_f32 v[22:23], v[22:23], v[48:49] op_sel_hi:[1,0]
	v_pk_mul_f32 v[24:25], v[24:25], v[48:49] op_sel_hi:[1,0]
	v_pk_mul_f32 v[20:21], v[20:21], v[48:49] op_sel_hi:[1,0]
	v_pk_mul_f32 v[18:19], v[130:131], v[18:19]
	s_waitcnt vmcnt(0)
	v_pk_mul_f32 v[48:49], v[44:45], v[28:29]
	v_pk_mul_f32 v[52:53], v[46:47], v[26:27]
	v_pk_mul_f32 v[44:45], v[44:45], v[50:51]
	v_pk_mul_f32 v[22:23], v[134:135], v[22:23]
	v_pk_mul_f32 v[20:21], v[128:129], v[20:21]
	v_pk_fma_f32 v[52:53], v[38:39], v[30:31], v[52:53] neg_lo:[0,0,1] neg_hi:[0,0,1]
	v_pk_fma_f32 v[48:49], v[36:37], v[50:51], v[48:49] neg_lo:[0,0,1] neg_hi:[0,0,1]
	v_pk_mul_f32 v[30:31], v[46:47], v[30:31]
	v_pk_fma_f32 v[28:29], v[36:37], v[28:29], v[44:45]
	v_pk_mul_f32 v[36:37], v[42:43], v[18:19]
	v_pk_mul_f32 v[24:25], v[132:133], v[24:25]
	v_pk_fma_f32 v[26:27], v[38:39], v[26:27], v[30:31]
	v_pk_mul_f32 v[30:31], v[40:41], v[20:21]
	v_pk_fma_f32 v[36:37], v[34:35], v[22:23], v[36:37] neg_lo:[0,0,1] neg_hi:[0,0,1]
	v_pk_mul_f32 v[22:23], v[42:43], v[22:23]
	v_pk_fma_f32 v[30:31], v[32:33], v[24:25], v[30:31] neg_lo:[0,0,1] neg_hi:[0,0,1]
	v_pk_mul_f32 v[24:25], v[40:41], v[24:25]
	v_pk_fma_f32 v[18:19], v[34:35], v[18:19], v[22:23]
	v_cvt_pk_bf16_f32 v22, v48, v49
	v_cvt_pk_bf16_f32 v23, v52, v53
	v_pk_fma_f32 v[20:21], v[32:33], v[20:21], v[24:25]
	v_mov_b32_e32 v248, v22
	v_mov_b32_e32 v249, v23
	v_cvt_pk_bf16_f32 v22, v28, v29
	v_cvt_pk_bf16_f32 v23, v26, v27
	v_mov_b32_e32 v250, v22
	v_mov_b32_e32 v251, v23
	v_cvt_pk_bf16_f32 v22, v30, v31
	v_cvt_pk_bf16_f32 v23, v36, v37
	v_mov_b32_e32 v244, v22
	v_mov_b32_e32 v245, v23
	v_cvt_pk_bf16_f32 v20, v20, v21
	v_cvt_pk_bf16_f32 v21, v18, v19
	v_mov_b32_e32 v246, v20
	v_mov_b32_e32 v247, v21
	v_and_b32_e32 v242, 16, v190
	v_mul_u32_u24_e32 v242, 3, v242
	v_lshrrev_b32_e32 v242, 1, v242
	v_mov_b32_e32 v243, 0
	v_lshl_add_u64 v[240:241], v[16:17], 0, v[242:243]
	v_permlane16_swap_b32 v248, v250
	v_permlane16_swap_b32 v249, v251
	v_permlane16_swap_b32 v244, v246
	v_permlane16_swap_b32 v245, v247
	flat_store_dwordx4 v[240:241], v[248:251]
	flat_store_dwordx4 v[240:241], v[244:247] offset:64
	v_bitop3_b32 v16, v158, s0, v199 bitop3:0xc8
	v_mov_b32_e32 v17, v145
	v_or_b32_e32 v32, 0x70, v158
	v_lshl_add_u64 v[18:19], v[160:161], 0, v[16:17]
	v_lshl_add_u64 v[16:17], v[162:163], 0, v[16:17]
	flat_load_dwordx4 v[20:23], v[18:19]
	flat_load_dwordx4 v[28:31], v[16:17]
	v_lshlrev_b32_e32 v16, 6, v32
	v_and_b32_e32 v16, 0xfc0, v16
	v_mov_b32_e32 v17, v145
	v_lshl_add_u64 v[18:19], v[160:161], 0, v[16:17]
	v_lshl_add_u64 v[24:25], v[162:163], 0, v[16:17]
	flat_load_dwordx4 v[16:19], v[18:19]
	s_nop 0
	flat_load_dwordx4 v[24:27], v[24:25]
	ds_read_b32 v42, v218 offset:448
	v_ashrrev_i32_e32 v33, 31, v32
	s_waitcnt lgkmcnt(0)
	v_pk_mul_f32 v[40:41], v[0:1], v[42:43] op_sel_hi:[1,0]
	v_pk_mul_f32 v[36:37], v[4:5], v[42:43] op_sel_hi:[1,0]
	v_pk_mul_f32 v[4:5], v[12:13], v[42:43] op_sel_hi:[1,0]
	v_mul_f32_e32 v12, v41, v41
	v_pk_mul_f32 v[38:39], v[2:3], v[42:43] op_sel_hi:[1,0]
	v_fmac_f32_e32 v12, v40, v40
	v_fmac_f32_e32 v12, v38, v38
	v_fmac_f32_e32 v12, v39, v39
	v_fmac_f32_e32 v12, v36, v36
	v_pk_mul_f32 v[34:35], v[6:7], v[42:43] op_sel_hi:[1,0]
	v_fmac_f32_e32 v12, v37, v37
	v_pk_mul_f32 v[8:9], v[8:9], v[42:43] op_sel_hi:[1,0]
	v_fmac_f32_e32 v12, v34, v34
	v_pk_mul_f32 v[6:7], v[10:11], v[42:43] op_sel_hi:[1,0]
	v_fmac_f32_e32 v12, v35, v35
	v_pk_mul_f32 v[10:11], v[8:9], v[8:9]
	v_pk_mul_f32 v[0:1], v[6:7], v[6:7]
	v_add_f32_e32 v10, v10, v12
	v_add_f32_e32 v10, v11, v10
	v_add_f32_e32 v0, v0, v10
	v_add_f32_e32 v12, v1, v0
	v_pk_mul_f32 v[10:11], v[4:5], v[4:5]
	v_pk_mul_f32 v[2:3], v[14:15], v[42:43] op_sel_hi:[1,0]
	v_add_f32_e32 v10, v10, v12
	v_pk_mul_f32 v[0:1], v[2:3], v[2:3]
	v_add_f32_e32 v10, v11, v10
	v_add_f32_e32 v0, v0, v10
	v_add_f32_e32 v0, v1, v0
	ds_bpermute_b32 v1, v216, v0
	s_waitcnt lgkmcnt(0)
	v_add_f32_e32 v10, v0, v1
	ds_bpermute_b32 v11, v217, v10
	s_and_saveexec_b64 s[2:3], vcc
	s_xor_b64 s[2:3], exec, s[2:3]
	v_lshlrev_b64 v[0:1], 8, v[32:33]
	v_lshl_add_u64 v[0:1], v[156:157], 0, v[0:1]
	s_mov_b64 s[6:7], 0x69dfc00
	v_lshl_add_u64 v[0:1], v[0:1], 0, s[6:7]
	s_andn2_saveexec_b64 s[2:3], s[2:3]
	s_cbranch_execz .LBB0_409
	v_lshlrev_b64 v[0:1], 10, v[32:33]
	v_lshl_add_u64 v[0:1], v[154:155], 0, v[0:1]
	s_branch .LBB0_409
